# speedup vs baseline: 1.0105x; 1.0062x over previous
; DEVINL float shx(float v, int m, int lane) { return __int_as_float(__builtin_amdgcn_ds_bpermute((lane ^ m) << 2, __float_as_int(v))); }
; DEVINL void phase_gemm_res(const Params& p, const u16* A, int lda, const u16* B, int K, const float* resid, char* smem, int wv) {
;     ...
; #pragma unroll
;     for (int ai = 0; ai < 2; ++ai)
; #pragma unroll
;       for (int m = 0; m < 4; ++m) {
;         int row = m0 + ai * 128 + wr * 64 + m * 16 + fr;
;         size_t off = (size_t)row * DM + n0 + wc * 32 + fq * 4;
;         size_t offw = (size_t)row * DM + n0 + wc * 32 + (fq & 1) * 16 + (fq >> 1) * 8;
;         float ss = 0.f;
; #pragma unroll
;         for (int bj = 0; bj < 2; ++bj) {
;           f32x4 vv[2];
; #pragma unroll
;           for (int n = 0; n < 2; ++n) {
;             float4 rv = *(const float4*)(resid + off + bj * 128 + n * 16);
;             f32x4 v = acc[ai][bj][m][n];
;             v[0] += rv.x; v[1] += rv.y; v[2] += rv.z; v[3] += rv.w;
;             float4 ov; ov.x = v[0]; ov.y = v[1]; ov.z = v[2]; ov.w = v[3];
;             *(float4*)(out + off + bj * 128 + n * 16) = ov;
;             ss += sumsq4(v);
;             vv[n] = v;
;           }
;           *(u32x4*)(xb + offw + bj * 128) = widen2(vv[0], vv[1]);
;         }
;         ss += shx(ss, 16, lane); ss += shx(ss, 32, lane);
;         if (fq == 0) part[(size_t)row * 32 + pn * 4 + wc] = ss;
;       }
.LBB0_854:
	s_ashr_i32 s0, s31, 2
	s_andn2_b32 s0, s0, 63
	v_or_b32_e32 v128, s0, v128
	s_bfe_u32 s29, s31, 0x20006
	v_add_u32_e32 v130, s28, v128
	s_lshl_b32 s0, s29, 5
	v_ashrrev_i32_e32 v131, 31, v130
	s_or_b32 s24, s24, s0
	v_lshrrev_b32_e32 v128, 2, v151
	v_lshlrev_b64 v[134:135], 11, v[130:131]
	v_and_b32_e32 v132, 12, v128
	v_lshl_add_u64 v[142:143], v[134:135], 0, s[24:25]
	v_or_b32_e32 v134, v142, v132
	v_mov_b32_e32 v135, v143
	v_readlane_b32 s40, v254, 2
	v_lshlrev_b64 v[138:139], 2, v[134:135]
	v_readlane_b32 s41, v254, 3
	v_lshl_add_u64 v[148:149], s[92:93], 0, v[138:139]
	s_lshl_b32 s0, s30, 2
	v_lshl_add_u64 v[146:147], s[40:41], 0, v[138:139]
	global_load_dwordx4 v[200:203], v[146:147], off
	global_load_dwordx4 v[204:207], v[146:147], off offset:64
	global_load_dwordx4 v[208:211], v[146:147], off offset:512
	global_load_dwordx4 v[212:215], v[146:147], off offset:576
	s_ashr_i32 s1, s0, 31
	s_lshl_b64 s[0:1], s[0:1], 2
	s_add_u32 s0, s60, s0
	s_addc_u32 s1, s61, s1
	s_lshl_b32 s28, s29, 2
	s_add_u32 s28, s0, s28
	s_addc_u32 s29, s1, 0
	v_readlane_b32 s42, v254, 4
	v_readlane_b32 s43, v254, 5
	v_readlane_b32 s44, v254, 6
	v_readlane_b32 s45, v254, 7
	v_readlane_b32 s46, v254, 8
	v_readlane_b32 s47, v254, 9
	v_readlane_b32 s48, v254, 10
	v_readlane_b32 s49, v254, 11
	v_readlane_b32 s50, v254, 12
	v_readlane_b32 s51, v254, 13
	v_readlane_b32 s52, v254, 14
	v_readlane_b32 s53, v254, 15
	v_readlane_b32 s54, v254, 16
	v_readlane_b32 s55, v254, 17
	s_waitcnt vmcnt(0)
	v_pk_add_f32 v[134:135], v[124:125], v[200:201]
	v_pk_add_f32 v[136:137], v[126:127], v[202:203]
	global_store_dwordx4 v[148:149], v[134:137], off
	v_and_b32_e32 v124, 16, v151
	v_and_or_b32 v124, v128, 8, v124
	v_lshlrev_b32_e32 v128, 1, v124
	v_lshl_add_u64 v[124:125], s[90:91], 0, v[128:129]
	v_lshl_add_u64 v[126:127], v[142:143], 1, v[124:125]
	v_cvt_pk_bf16_f32 v142, v134, v135
	v_cvt_pk_bf16_f32 v143, v136, v137
	v_pk_add_f32 v[138:139], v[116:117], v[204:205]
	v_pk_add_f32 v[140:141], v[118:119], v[206:207]
	v_cvt_pk_bf16_f32 v144, v138, v139
	v_cvt_pk_bf16_f32 v145, v140, v141
	s_nop 0
	v_permlane16_swap_b32_e32 v142, v144
	v_permlane16_swap_b32_e32 v143, v145
	global_store_dwordx4 v[148:149], v[138:141], off offset:64
	global_store_dwordx4 v[126:127], v[142:145], off
	v_pk_add_f32 v[120:121], v[120:121], v[208:209]
	v_pk_add_f32 v[122:123], v[122:123], v[210:211]
	global_store_dwordx4 v[148:149], v[120:123], off offset:512
	v_and_b32_e32 v116, 63, v151
	v_lshlrev_b32_e32 v118, 2, v116
	v_cmp_gt_u32_e32 vcc, 16, v116
	v_xor_b32_e32 v117, 64, v118
	v_xor_b32_e32 v116, 0x80, v118
	v_pk_mul_f32 v[118:119], v[134:135], v[134:135]
	v_pk_mul_f32 v[134:135], v[136:137], v[136:137]
	v_add_f32_e32 v118, v118, v119
	v_add_f32_e32 v118, v134, v118
	v_add_f32_e32 v128, v135, v118
	v_pk_mul_f32 v[118:119], v[138:139], v[138:139]
	v_pk_mul_f32 v[134:135], v[140:141], v[140:141]
	v_add_f32_e32 v118, v118, v119
	v_add_f32_e32 v118, v134, v118
	v_add_f32_e32 v118, v135, v118
	v_pk_mul_f32 v[134:135], v[120:121], v[120:121]
	v_add_f32_e32 v119, v128, v118
	v_pk_mul_f32 v[136:137], v[122:123], v[122:123]
	v_cvt_pk_bf16_f32 v118, v120, v121
	v_add_f32_e32 v120, v134, v135
	v_add_f32_e32 v120, v136, v120
	v_add_f32_e32 v120, v137, v120
	v_add_f32_e32 v119, v119, v120
	v_pk_add_f32 v[112:113], v[112:113], v[212:213]
	v_pk_add_f32 v[114:115], v[114:115], v[214:215]
	v_pk_mul_f32 v[120:121], v[112:113], v[112:113]
	v_pk_mul_f32 v[134:135], v[114:115], v[114:115]
	v_add_f32_e32 v120, v120, v121
	v_add_f32_e32 v120, v134, v120
	v_add_f32_e32 v120, v135, v120
	v_add_f32_e32 v128, v119, v120
	ds_bpermute_b32 v133, v117, v128
	global_store_dwordx4 v[148:149], v[112:115], off offset:576
	v_cvt_pk_bf16_f32 v120, v112, v113
	v_cvt_pk_bf16_f32 v119, v122, v123
	v_cvt_pk_bf16_f32 v121, v114, v115
	s_waitcnt lgkmcnt(0)
	v_add_f32_e32 v112, v128, v133
	ds_bpermute_b32 v113, v116, v112
	v_permlane16_swap_b32_e32 v118, v120
	v_permlane16_swap_b32_e32 v119, v121
	global_store_dwordx4 v[126:127], v[118:121], off offset:256
	s_and_saveexec_b64 s[30:31], vcc
	s_cbranch_execz .LBB0_856
	v_lshlrev_b64 v[114:115], 7, v[130:131]
	v_lshl_add_u64 v[114:115], s[28:29], 0, v[114:115]
	s_waitcnt lgkmcnt(0)
	v_add_f32_e32 v112, v112, v113
	global_store_dword v[114:115], v112, off
; DEVINL float shx(float v, int m, int lane) { return __int_as_float(__builtin_amdgcn_ds_bpermute((lane ^ m) << 2, __float_as_int(v))); }
; DEVINL void phase_gemm_res(const Params& p, const u16* A, int lda, const u16* B, int K, const float* resid, char* smem, int wv) {
;     ...
; #pragma unroll
;     for (int ai = 0; ai < 2; ++ai)
; #pragma unroll
;       for (int m = 0; m < 4; ++m) {
;         int row = m0 + ai * 128 + wr * 64 + m * 16 + fr;
;         size_t off = (size_t)row * DM + n0 + wc * 32 + fq * 4;
;         size_t offw = (size_t)row * DM + n0 + wc * 32 + (fq & 1) * 16 + (fq >> 1) * 8;
;         float ss = 0.f;
; #pragma unroll
;         for (int bj = 0; bj < 2; ++bj) {
;           f32x4 vv[2];
; #pragma unroll
;           for (int n = 0; n < 2; ++n) {
;             float4 rv = *(const float4*)(resid + off + bj * 128 + n * 16);
;             f32x4 v = acc[ai][bj][m][n];
;             v[0] += rv.x; v[1] += rv.y; v[2] += rv.z; v[3] += rv.w;
;             float4 ov; ov.x = v[0]; ov.y = v[1]; ov.z = v[2]; ov.w = v[3];
;             *(float4*)(out + off + bj * 128 + n * 16) = ov;
;             ss += sumsq4(v);
;             vv[n] = v;
;           }
;           *(u32x4*)(xb + offw + bj * 128) = widen2(vv[0], vv[1]);
;         }
;         ss += shx(ss, 16, lane); ss += shx(ss, 32, lane);
;         if (fq == 0) part[(size_t)row * 32 + pn * 4 + wc] = ss;
;       }
.LBB0_856:
	s_or_b64 exec, exec, s[30:31]
	v_or_b32_e32 v112, 16, v130
	s_waitcnt lgkmcnt(0)
	v_ashrrev_i32_e32 v113, 31, v112
	v_lshlrev_b64 v[114:115], 11, v[112:113]
	v_lshl_add_u64 v[114:115], v[114:115], 0, s[24:25]
	v_or_b32_e32 v118, v114, v132
	v_mov_b32_e32 v119, v115
	v_readlane_b32 s40, v254, 2
	v_lshlrev_b64 v[122:123], 2, v[118:119]
	v_readlane_b32 s41, v254, 3
	v_lshl_add_u64 v[114:115], v[114:115], 1, v[124:125]
	v_readlane_b32 s42, v254, 4
	v_lshl_add_u64 v[126:127], s[40:41], 0, v[122:123]
	global_load_dwordx4 v[200:203], v[126:127], off
	global_load_dwordx4 v[204:207], v[126:127], off offset:64
	global_load_dwordx4 v[208:211], v[126:127], off offset:512
	global_load_dwordx4 v[212:215], v[126:127], off offset:576
	v_lshl_add_u64 v[122:123], s[92:93], 0, v[122:123]
	v_readlane_b32 s43, v254, 5
	v_readlane_b32 s44, v254, 6
	v_readlane_b32 s45, v254, 7
	v_readlane_b32 s46, v254, 8
	v_readlane_b32 s47, v254, 9
	v_readlane_b32 s48, v254, 10
	v_readlane_b32 s49, v254, 11
	v_readlane_b32 s50, v254, 12
	v_readlane_b32 s51, v254, 13
	v_readlane_b32 s52, v254, 14
	v_readlane_b32 s53, v254, 15
	v_readlane_b32 s54, v254, 16
	v_readlane_b32 s55, v254, 17
	s_waitcnt vmcnt(0)
	v_pk_add_f32 v[108:109], v[108:109], v[200:201]
	v_pk_add_f32 v[110:111], v[110:111], v[202:203]
	global_store_dwordx4 v[122:123], v[108:111], off
	v_cvt_pk_bf16_f32 v134, v108, v109
	v_cvt_pk_bf16_f32 v135, v110, v111
	v_pk_mul_f32 v[108:109], v[108:109], v[108:109]
	v_pk_mul_f32 v[110:111], v[110:111], v[110:111]
	v_add_f32_e32 v108, v108, v109
	v_add_f32_e32 v108, v110, v108
	v_add_f32_e32 v108, v111, v108
	v_pk_add_f32 v[100:101], v[100:101], v[204:205]
	v_pk_add_f32 v[102:103], v[102:103], v[206:207]
	v_cvt_pk_bf16_f32 v136, v100, v101
	v_cvt_pk_bf16_f32 v137, v102, v103
	s_nop 0
	v_permlane16_swap_b32_e32 v134, v136
	v_permlane16_swap_b32_e32 v135, v137
	global_store_dwordx4 v[122:123], v[100:103], off offset:64
	global_store_dwordx4 v[114:115], v[134:137], off
	s_nop 0
	v_pk_mul_f32 v[100:101], v[100:101], v[100:101]
	v_pk_mul_f32 v[102:103], v[102:103], v[102:103]
	v_add_f32_e32 v100, v100, v101
	v_add_f32_e32 v100, v102, v100
	v_add_f32_e32 v100, v103, v100
	v_add_f32_e32 v101, v108, v100
	v_pk_add_f32 v[104:105], v[104:105], v[208:209]
	v_pk_add_f32 v[106:107], v[106:107], v[210:211]
	global_store_dwordx4 v[122:123], v[104:107], off offset:512
	v_pk_mul_f32 v[102:103], v[104:105], v[104:105]
	v_pk_mul_f32 v[108:109], v[106:107], v[106:107]
	v_add_f32_e32 v102, v102, v103
	v_add_f32_e32 v102, v108, v102
	v_add_f32_e32 v102, v109, v102
	v_add_f32_e32 v101, v101, v102
	v_cvt_pk_bf16_f32 v100, v104, v105
	v_pk_add_f32 v[96:97], v[96:97], v[212:213]
	v_pk_add_f32 v[98:99], v[98:99], v[214:215]
	v_pk_mul_f32 v[102:103], v[96:97], v[96:97]
	v_pk_mul_f32 v[104:105], v[98:99], v[98:99]
	v_add_f32_e32 v102, v102, v103
	v_add_f32_e32 v102, v104, v102
	v_add_f32_e32 v102, v105, v102
	v_add_f32_e32 v104, v101, v102
	ds_bpermute_b32 v105, v117, v104
	global_store_dwordx4 v[122:123], v[96:99], off offset:576
	v_cvt_pk_bf16_f32 v102, v96, v97
	v_cvt_pk_bf16_f32 v101, v106, v107
	v_cvt_pk_bf16_f32 v103, v98, v99
	s_waitcnt lgkmcnt(0)
	v_add_f32_e32 v96, v104, v105
	ds_bpermute_b32 v97, v116, v96
	v_permlane16_swap_b32_e32 v100, v102
	v_permlane16_swap_b32_e32 v101, v103
	global_store_dwordx4 v[114:115], v[100:103], off offset:256
	s_and_saveexec_b64 s[30:31], vcc
	s_cbranch_execz .LBB0_858
	v_lshlrev_b64 v[98:99], 7, v[112:113]
	v_lshl_add_u64 v[98:99], s[28:29], 0, v[98:99]
	s_waitcnt lgkmcnt(0)
	v_add_f32_e32 v96, v96, v97
	global_store_dword v[98:99], v96, off
.LBB0_858:
	s_or_b64 exec, exec, s[30:31]
	v_or_b32_e32 v96, 32, v130
	s_waitcnt lgkmcnt(0)
	v_ashrrev_i32_e32 v97, 31, v96
	v_lshlrev_b64 v[98:99], 11, v[96:97]
	v_lshl_add_u64 v[102:103], v[98:99], 0, s[24:25]
	v_or_b32_e32 v98, v102, v132
	v_mov_b32_e32 v99, v103
	v_readlane_b32 s40, v254, 2
	v_lshlrev_b64 v[104:105], 2, v[98:99]
	v_readlane_b32 s41, v254, 3
	v_lshl_add_u64 v[108:109], s[92:93], 0, v[104:105]
	v_lshl_add_u64 v[110:111], v[102:103], 1, v[124:125]
	v_lshl_add_u64 v[106:107], s[40:41], 0, v[104:105]
	global_load_dwordx4 v[200:203], v[106:107], off
	global_load_dwordx4 v[204:207], v[106:107], off offset:64
	global_load_dwordx4 v[208:211], v[106:107], off offset:512
	global_load_dwordx4 v[212:215], v[106:107], off offset:576
	v_readlane_b32 s42, v254, 4
	v_readlane_b32 s43, v254, 5
	v_readlane_b32 s44, v254, 6
	v_readlane_b32 s45, v254, 7
	v_readlane_b32 s46, v254, 8
	v_readlane_b32 s47, v254, 9
	v_readlane_b32 s48, v254, 10
	v_readlane_b32 s49, v254, 11
	v_readlane_b32 s50, v254, 12
	v_readlane_b32 s51, v254, 13
	v_readlane_b32 s52, v254, 14
	v_readlane_b32 s53, v254, 15
	v_readlane_b32 s54, v254, 16
	v_readlane_b32 s55, v254, 17
	s_waitcnt vmcnt(0)
	v_pk_add_f32 v[92:93], v[92:93], v[200:201]
	v_pk_add_f32 v[94:95], v[94:95], v[202:203]
	global_store_dwordx4 v[108:109], v[92:95], off
	v_cvt_pk_bf16_f32 v102, v92, v93
	v_cvt_pk_bf16_f32 v103, v94, v95
	v_pk_mul_f32 v[92:93], v[92:93], v[92:93]
	v_pk_mul_f32 v[94:95], v[94:95], v[94:95]
	v_add_f32_e32 v92, v92, v93
	v_add_f32_e32 v92, v94, v92
	v_add_f32_e32 v92, v95, v92
	v_pk_add_f32 v[84:85], v[84:85], v[204:205]
	v_pk_add_f32 v[86:87], v[86:87], v[206:207]
	v_cvt_pk_bf16_f32 v104, v84, v85
	v_cvt_pk_bf16_f32 v105, v86, v87
	s_nop 0
	v_permlane16_swap_b32_e32 v102, v104
	v_permlane16_swap_b32_e32 v103, v105
	global_store_dwordx4 v[108:109], v[84:87], off offset:64
	global_store_dwordx4 v[110:111], v[102:105], off
	s_nop 0
	v_pk_mul_f32 v[84:85], v[84:85], v[84:85]
	v_pk_mul_f32 v[86:87], v[86:87], v[86:87]
	v_add_f32_e32 v84, v84, v85
	v_add_f32_e32 v84, v86, v84
	v_add_f32_e32 v84, v87, v84
	v_add_f32_e32 v85, v92, v84
	v_pk_add_f32 v[88:89], v[88:89], v[208:209]
	v_pk_add_f32 v[90:91], v[90:91], v[210:211]
	global_store_dwordx4 v[108:109], v[88:91], off offset:512
	v_pk_mul_f32 v[86:87], v[88:89], v[88:89]
	v_pk_mul_f32 v[92:93], v[90:91], v[90:91]
	v_add_f32_e32 v86, v86, v87
	v_add_f32_e32 v86, v92, v86
	v_add_f32_e32 v86, v93, v86
	v_add_f32_e32 v85, v85, v86
	v_cvt_pk_bf16_f32 v84, v88, v89
	v_pk_add_f32 v[80:81], v[80:81], v[212:213]
	v_pk_add_f32 v[82:83], v[82:83], v[214:215]
	v_pk_mul_f32 v[86:87], v[80:81], v[80:81]
	v_pk_mul_f32 v[88:89], v[82:83], v[82:83]
	v_add_f32_e32 v86, v86, v87
	v_add_f32_e32 v86, v88, v86
	v_add_f32_e32 v86, v89, v86
	v_add_f32_e32 v88, v85, v86
	ds_bpermute_b32 v89, v117, v88
	global_store_dwordx4 v[108:109], v[80:83], off offset:576
	v_cvt_pk_bf16_f32 v86, v80, v81
	v_cvt_pk_bf16_f32 v85, v90, v91
	v_cvt_pk_bf16_f32 v87, v82, v83
	s_waitcnt lgkmcnt(0)
	v_add_f32_e32 v80, v88, v89
	ds_bpermute_b32 v81, v116, v80
	v_permlane16_swap_b32_e32 v84, v86
	v_permlane16_swap_b32_e32 v85, v87
	global_store_dwordx4 v[110:111], v[84:87], off offset:256
	s_and_saveexec_b64 s[30:31], vcc
	s_cbranch_execz .LBB0_860
	v_lshlrev_b64 v[82:83], 7, v[96:97]
	v_lshl_add_u64 v[82:83], s[28:29], 0, v[82:83]
	s_waitcnt lgkmcnt(0)
	v_add_f32_e32 v80, v80, v81
	global_store_dword v[82:83], v80, off
; DEVINL float shx(float v, int m, int lane) { return __int_as_float(__builtin_amdgcn_ds_bpermute((lane ^ m) << 2, __float_as_int(v))); }
; DEVINL void phase_gemm_res(const Params& p, const u16* A, int lda, const u16* B, int K, const float* resid, char* smem, int wv) {
;     ...
; #pragma unroll
;     for (int ai = 0; ai < 2; ++ai)
; #pragma unroll
;       for (int m = 0; m < 4; ++m) {
;         int row = m0 + ai * 128 + wr * 64 + m * 16 + fr;
;         size_t off = (size_t)row * DM + n0 + wc * 32 + fq * 4;
;         size_t offw = (size_t)row * DM + n0 + wc * 32 + (fq & 1) * 16 + (fq >> 1) * 8;
;         float ss = 0.f;
; #pragma unroll
;         for (int bj = 0; bj < 2; ++bj) {
;           f32x4 vv[2];
; #pragma unroll
;           for (int n = 0; n < 2; ++n) {
;             float4 rv = *(const float4*)(resid + off + bj * 128 + n * 16);
;             f32x4 v = acc[ai][bj][m][n];
;             v[0] += rv.x; v[1] += rv.y; v[2] += rv.z; v[3] += rv.w;
;             float4 ov; ov.x = v[0]; ov.y = v[1]; ov.z = v[2]; ov.w = v[3];
;             *(float4*)(out + off + bj * 128 + n * 16) = ov;
;             ss += sumsq4(v);
;             vv[n] = v;
;           }
;           *(u32x4*)(xb + offw + bj * 128) = widen2(vv[0], vv[1]);
;         }
;         ss += shx(ss, 16, lane); ss += shx(ss, 32, lane);
;         if (fq == 0) part[(size_t)row * 32 + pn * 4 + wc] = ss;
;       }
.LBB0_860:
	s_or_b64 exec, exec, s[30:31]
	v_or_b32_e32 v80, 48, v130
	s_waitcnt lgkmcnt(0)
	v_ashrrev_i32_e32 v81, 31, v80
	v_lshlrev_b64 v[82:83], 11, v[80:81]
	v_lshl_add_u64 v[86:87], v[82:83], 0, s[24:25]
	v_or_b32_e32 v82, v86, v132
	v_mov_b32_e32 v83, v87
	v_readlane_b32 s40, v254, 2
	v_lshlrev_b64 v[88:89], 2, v[82:83]
	v_readlane_b32 s41, v254, 3
	v_lshl_add_u64 v[92:93], s[92:93], 0, v[88:89]
	v_lshl_add_u64 v[94:95], v[86:87], 1, v[124:125]
	v_lshl_add_u64 v[90:91], s[40:41], 0, v[88:89]
	global_load_dwordx4 v[200:203], v[90:91], off
	global_load_dwordx4 v[204:207], v[90:91], off offset:64
	global_load_dwordx4 v[208:211], v[90:91], off offset:512
	global_load_dwordx4 v[212:215], v[90:91], off offset:576
	v_readlane_b32 s42, v254, 4
	v_readlane_b32 s43, v254, 5
	v_readlane_b32 s44, v254, 6
	v_readlane_b32 s45, v254, 7
	v_readlane_b32 s46, v254, 8
	v_readlane_b32 s47, v254, 9
	v_readlane_b32 s48, v254, 10
	v_readlane_b32 s49, v254, 11
	v_readlane_b32 s50, v254, 12
	v_readlane_b32 s51, v254, 13
	v_readlane_b32 s52, v254, 14
	v_readlane_b32 s53, v254, 15
	v_readlane_b32 s54, v254, 16
	v_readlane_b32 s55, v254, 17
	s_waitcnt vmcnt(0)
	v_pk_add_f32 v[76:77], v[76:77], v[200:201]
	v_pk_add_f32 v[78:79], v[78:79], v[202:203]
	global_store_dwordx4 v[92:93], v[76:79], off
	v_cvt_pk_bf16_f32 v86, v76, v77
	v_cvt_pk_bf16_f32 v87, v78, v79
	v_pk_mul_f32 v[76:77], v[76:77], v[76:77]
	v_pk_mul_f32 v[78:79], v[78:79], v[78:79]
	v_add_f32_e32 v76, v76, v77
	v_add_f32_e32 v76, v78, v76
	v_add_f32_e32 v76, v79, v76
	v_pk_add_f32 v[68:69], v[68:69], v[204:205]
	v_pk_add_f32 v[70:71], v[70:71], v[206:207]
	v_cvt_pk_bf16_f32 v88, v68, v69
	v_cvt_pk_bf16_f32 v89, v70, v71
	s_nop 0
	v_permlane16_swap_b32_e32 v86, v88
	v_permlane16_swap_b32_e32 v87, v89
	global_store_dwordx4 v[92:93], v[68:71], off offset:64
	global_store_dwordx4 v[94:95], v[86:89], off
	s_nop 0
	v_pk_mul_f32 v[68:69], v[68:69], v[68:69]
	v_pk_mul_f32 v[70:71], v[70:71], v[70:71]
	v_add_f32_e32 v68, v68, v69
	v_add_f32_e32 v68, v70, v68
	v_add_f32_e32 v68, v71, v68
	v_add_f32_e32 v69, v76, v68
	v_pk_add_f32 v[72:73], v[72:73], v[208:209]
	v_pk_add_f32 v[74:75], v[74:75], v[210:211]
	global_store_dwordx4 v[92:93], v[72:75], off offset:512
	v_pk_mul_f32 v[70:71], v[72:73], v[72:73]
	v_pk_mul_f32 v[76:77], v[74:75], v[74:75]
	v_add_f32_e32 v70, v70, v71
	v_add_f32_e32 v70, v76, v70
	v_add_f32_e32 v70, v77, v70
	v_add_f32_e32 v69, v69, v70
	v_cvt_pk_bf16_f32 v68, v72, v73
	v_pk_add_f32 v[64:65], v[64:65], v[212:213]
	v_pk_add_f32 v[66:67], v[66:67], v[214:215]
	v_pk_mul_f32 v[70:71], v[64:65], v[64:65]
	v_pk_mul_f32 v[72:73], v[66:67], v[66:67]
	v_add_f32_e32 v70, v70, v71
	v_add_f32_e32 v70, v72, v70
	v_add_f32_e32 v70, v73, v70
	v_add_f32_e32 v72, v69, v70
	ds_bpermute_b32 v73, v117, v72
	global_store_dwordx4 v[92:93], v[64:67], off offset:576
	v_cvt_pk_bf16_f32 v70, v64, v65
	v_cvt_pk_bf16_f32 v69, v74, v75
	v_cvt_pk_bf16_f32 v71, v66, v67
	s_waitcnt lgkmcnt(0)
	v_add_f32_e32 v64, v72, v73
	ds_bpermute_b32 v65, v116, v64
	v_permlane16_swap_b32_e32 v68, v70
	v_permlane16_swap_b32_e32 v69, v71
	global_store_dwordx4 v[94:95], v[68:71], off offset:256
	s_and_saveexec_b64 s[30:31], vcc
	s_cbranch_execz .LBB0_862
	v_lshlrev_b64 v[66:67], 7, v[80:81]
	v_lshl_add_u64 v[66:67], s[28:29], 0, v[66:67]
	s_waitcnt lgkmcnt(0)
	v_add_f32_e32 v64, v64, v65
	global_store_dword v[66:67], v64, off
.LBB0_862:
	s_or_b64 exec, exec, s[30:31]
	v_add_u32_e32 v64, 0x80, v130
	s_waitcnt lgkmcnt(0)
	v_ashrrev_i32_e32 v65, 31, v64
	v_lshlrev_b64 v[66:67], 11, v[64:65]
	v_lshl_add_u64 v[70:71], v[66:67], 0, s[24:25]
	v_or_b32_e32 v66, v70, v132
	v_mov_b32_e32 v67, v71
	v_readlane_b32 s40, v254, 2
	v_lshlrev_b64 v[72:73], 2, v[66:67]
	v_readlane_b32 s41, v254, 3
	v_lshl_add_u64 v[76:77], s[92:93], 0, v[72:73]
	v_lshl_add_u64 v[78:79], v[70:71], 1, v[124:125]
	v_lshl_add_u64 v[74:75], s[40:41], 0, v[72:73]
	global_load_dwordx4 v[200:203], v[74:75], off
	global_load_dwordx4 v[204:207], v[74:75], off offset:64
	global_load_dwordx4 v[208:211], v[74:75], off offset:512
	global_load_dwordx4 v[212:215], v[74:75], off offset:576
	v_readlane_b32 s42, v254, 4
	v_readlane_b32 s43, v254, 5
	v_readlane_b32 s44, v254, 6
	v_readlane_b32 s45, v254, 7
	v_readlane_b32 s46, v254, 8
	v_readlane_b32 s47, v254, 9
	v_readlane_b32 s48, v254, 10
	v_readlane_b32 s49, v254, 11
	v_readlane_b32 s50, v254, 12
	v_readlane_b32 s51, v254, 13
	v_readlane_b32 s52, v254, 14
	v_readlane_b32 s53, v254, 15
	v_readlane_b32 s54, v254, 16
	v_readlane_b32 s55, v254, 17
	s_waitcnt vmcnt(0)
	v_pk_add_f32 v[60:61], v[60:61], v[200:201]
	v_pk_add_f32 v[62:63], v[62:63], v[202:203]
	global_store_dwordx4 v[76:77], v[60:63], off
	v_cvt_pk_bf16_f32 v70, v60, v61
	v_cvt_pk_bf16_f32 v71, v62, v63
	v_pk_mul_f32 v[60:61], v[60:61], v[60:61]
	v_pk_mul_f32 v[62:63], v[62:63], v[62:63]
	v_add_f32_e32 v60, v60, v61
	v_add_f32_e32 v60, v62, v60
	v_add_f32_e32 v60, v63, v60
	v_pk_add_f32 v[56:57], v[56:57], v[204:205]
	v_pk_add_f32 v[58:59], v[58:59], v[206:207]
	v_cvt_pk_bf16_f32 v72, v56, v57
	v_cvt_pk_bf16_f32 v73, v58, v59
	s_nop 0
	v_permlane16_swap_b32_e32 v70, v72
	v_permlane16_swap_b32_e32 v71, v73
	global_store_dwordx4 v[76:77], v[56:59], off offset:64
	global_store_dwordx4 v[78:79], v[70:73], off
	s_nop 0
	v_pk_mul_f32 v[56:57], v[56:57], v[56:57]
	v_pk_mul_f32 v[58:59], v[58:59], v[58:59]
	v_add_f32_e32 v56, v56, v57
	v_add_f32_e32 v56, v58, v56
	v_add_f32_e32 v56, v59, v56
	v_add_f32_e32 v60, v60, v56
	v_pk_add_f32 v[52:53], v[52:53], v[208:209]
	v_pk_add_f32 v[54:55], v[54:55], v[210:211]
	global_store_dwordx4 v[76:77], v[52:55], off offset:512
	v_pk_mul_f32 v[56:57], v[52:53], v[52:53]
	v_pk_mul_f32 v[58:59], v[54:55], v[54:55]
	v_cvt_pk_bf16_f32 v52, v52, v53
	v_add_f32_e32 v53, v56, v57
	v_add_f32_e32 v53, v58, v53
	v_add_f32_e32 v53, v59, v53
	v_add_f32_e32 v53, v60, v53
	v_pk_add_f32 v[48:49], v[48:49], v[212:213]
	v_pk_add_f32 v[50:51], v[50:51], v[214:215]
	v_pk_mul_f32 v[56:57], v[48:49], v[48:49]
	v_pk_mul_f32 v[58:59], v[50:51], v[50:51]
	v_add_f32_e32 v56, v56, v57
	v_add_f32_e32 v56, v58, v56
	v_add_f32_e32 v56, v59, v56
	v_add_f32_e32 v56, v53, v56
	ds_bpermute_b32 v57, v117, v56
	v_cvt_pk_bf16_f32 v53, v54, v55
	global_store_dwordx4 v[76:77], v[48:51], off offset:576
	v_cvt_pk_bf16_f32 v54, v48, v49
	v_cvt_pk_bf16_f32 v55, v50, v51
	s_waitcnt lgkmcnt(0)
	v_add_f32_e32 v48, v56, v57
	ds_bpermute_b32 v49, v116, v48
	v_permlane16_swap_b32_e32 v52, v54
	v_permlane16_swap_b32_e32 v53, v55
	global_store_dwordx4 v[78:79], v[52:55], off offset:256
	s_and_saveexec_b64 s[30:31], vcc
	s_cbranch_execz .LBB0_864
	v_lshlrev_b64 v[50:51], 7, v[64:65]
	v_lshl_add_u64 v[50:51], s[28:29], 0, v[50:51]
	s_waitcnt lgkmcnt(0)
	v_add_f32_e32 v48, v48, v49
	global_store_dword v[50:51], v48, off
; DEVINL float shx(float v, int m, int lane) { return __int_as_float(__builtin_amdgcn_ds_bpermute((lane ^ m) << 2, __float_as_int(v))); }
; DEVINL void phase_gemm_res(const Params& p, const u16* A, int lda, const u16* B, int K, const float* resid, char* smem, int wv) {
;     ...
; #pragma unroll
;     for (int ai = 0; ai < 2; ++ai)
; #pragma unroll
;       for (int m = 0; m < 4; ++m) {
;         int row = m0 + ai * 128 + wr * 64 + m * 16 + fr;
;         size_t off = (size_t)row * DM + n0 + wc * 32 + fq * 4;
;         size_t offw = (size_t)row * DM + n0 + wc * 32 + (fq & 1) * 16 + (fq >> 1) * 8;
;         float ss = 0.f;
; #pragma unroll
;         for (int bj = 0; bj < 2; ++bj) {
;           f32x4 vv[2];
; #pragma unroll
;           for (int n = 0; n < 2; ++n) {
;             float4 rv = *(const float4*)(resid + off + bj * 128 + n * 16);
;             f32x4 v = acc[ai][bj][m][n];
;             v[0] += rv.x; v[1] += rv.y; v[2] += rv.z; v[3] += rv.w;
;             float4 ov; ov.x = v[0]; ov.y = v[1]; ov.z = v[2]; ov.w = v[3];
;             *(float4*)(out + off + bj * 128 + n * 16) = ov;
;             ss += sumsq4(v);
;             vv[n] = v;
;           }
;           *(u32x4*)(xb + offw + bj * 128) = widen2(vv[0], vv[1]);
;         }
;         ss += shx(ss, 16, lane); ss += shx(ss, 32, lane);
;         if (fq == 0) part[(size_t)row * 32 + pn * 4 + wc] = ss;
;       }
.LBB0_864:
	s_or_b64 exec, exec, s[30:31]
	v_add_u32_e32 v48, 0x90, v130
	s_waitcnt lgkmcnt(0)
	v_ashrrev_i32_e32 v49, 31, v48
	v_lshlrev_b64 v[50:51], 11, v[48:49]
	v_lshl_add_u64 v[54:55], v[50:51], 0, s[24:25]
	v_or_b32_e32 v50, v54, v132
	v_mov_b32_e32 v51, v55
	v_readlane_b32 s40, v254, 2
	v_lshlrev_b64 v[56:57], 2, v[50:51]
	v_readlane_b32 s41, v254, 3
	v_lshl_add_u64 v[60:61], s[92:93], 0, v[56:57]
	v_lshl_add_u64 v[62:63], v[54:55], 1, v[124:125]
	v_lshl_add_u64 v[58:59], s[40:41], 0, v[56:57]
	global_load_dwordx4 v[200:203], v[58:59], off
	global_load_dwordx4 v[204:207], v[58:59], off offset:64
	global_load_dwordx4 v[208:211], v[58:59], off offset:512
	global_load_dwordx4 v[212:215], v[58:59], off offset:576
	v_readlane_b32 s42, v254, 4
	v_readlane_b32 s43, v254, 5
	v_readlane_b32 s44, v254, 6
	v_readlane_b32 s45, v254, 7
	v_readlane_b32 s46, v254, 8
	v_readlane_b32 s47, v254, 9
	v_readlane_b32 s48, v254, 10
	v_readlane_b32 s49, v254, 11
	v_readlane_b32 s50, v254, 12
	v_readlane_b32 s51, v254, 13
	v_readlane_b32 s52, v254, 14
	v_readlane_b32 s53, v254, 15
	v_readlane_b32 s54, v254, 16
	v_readlane_b32 s55, v254, 17
	s_waitcnt vmcnt(0)
	v_pk_add_f32 v[44:45], v[44:45], v[200:201]
	v_pk_add_f32 v[46:47], v[46:47], v[202:203]
	global_store_dwordx4 v[60:61], v[44:47], off
	v_cvt_pk_bf16_f32 v54, v44, v45
	v_cvt_pk_bf16_f32 v55, v46, v47
	v_pk_mul_f32 v[44:45], v[44:45], v[44:45]
	v_pk_mul_f32 v[46:47], v[46:47], v[46:47]
	v_add_f32_e32 v44, v44, v45
	v_add_f32_e32 v44, v46, v44
	v_add_f32_e32 v44, v47, v44
	v_pk_add_f32 v[40:41], v[40:41], v[204:205]
	v_pk_add_f32 v[42:43], v[42:43], v[206:207]
	v_cvt_pk_bf16_f32 v56, v40, v41
	v_cvt_pk_bf16_f32 v57, v42, v43
	s_nop 0
	v_permlane16_swap_b32_e32 v54, v56
	v_permlane16_swap_b32_e32 v55, v57
	global_store_dwordx4 v[60:61], v[40:43], off offset:64
	global_store_dwordx4 v[62:63], v[54:57], off
	s_nop 0
	v_pk_mul_f32 v[40:41], v[40:41], v[40:41]
	v_pk_mul_f32 v[42:43], v[42:43], v[42:43]
	v_add_f32_e32 v40, v40, v41
	v_add_f32_e32 v40, v42, v40
	v_add_f32_e32 v40, v43, v40
	v_add_f32_e32 v44, v44, v40
	v_pk_add_f32 v[36:37], v[36:37], v[208:209]
	v_pk_add_f32 v[38:39], v[38:39], v[210:211]
	global_store_dwordx4 v[60:61], v[36:39], off offset:512
	v_pk_mul_f32 v[40:41], v[36:37], v[36:37]
	v_pk_mul_f32 v[42:43], v[38:39], v[38:39]
	v_cvt_pk_bf16_f32 v36, v36, v37
	v_add_f32_e32 v37, v40, v41
	v_add_f32_e32 v37, v42, v37
	v_add_f32_e32 v37, v43, v37
	v_add_f32_e32 v37, v44, v37
	v_pk_add_f32 v[32:33], v[32:33], v[212:213]
	v_pk_add_f32 v[34:35], v[34:35], v[214:215]
	v_pk_mul_f32 v[40:41], v[32:33], v[32:33]
	v_pk_mul_f32 v[42:43], v[34:35], v[34:35]
	v_add_f32_e32 v40, v40, v41
	v_add_f32_e32 v40, v42, v40
	v_add_f32_e32 v40, v43, v40
	v_add_f32_e32 v40, v37, v40
	ds_bpermute_b32 v41, v117, v40
	v_cvt_pk_bf16_f32 v37, v38, v39
	global_store_dwordx4 v[60:61], v[32:35], off offset:576
	v_cvt_pk_bf16_f32 v38, v32, v33
	v_cvt_pk_bf16_f32 v39, v34, v35
	s_waitcnt lgkmcnt(0)
	v_add_f32_e32 v32, v40, v41
	ds_bpermute_b32 v33, v116, v32
	v_permlane16_swap_b32_e32 v36, v38
	v_permlane16_swap_b32_e32 v37, v39
	global_store_dwordx4 v[62:63], v[36:39], off offset:256
	s_and_saveexec_b64 s[30:31], vcc
	s_cbranch_execz .LBB0_866
	v_lshlrev_b64 v[34:35], 7, v[48:49]
	v_lshl_add_u64 v[34:35], s[28:29], 0, v[34:35]
	s_waitcnt lgkmcnt(0)
	v_add_f32_e32 v32, v32, v33
	global_store_dword v[34:35], v32, off
; DEVINL float shx(float v, int m, int lane) { return __int_as_float(__builtin_amdgcn_ds_bpermute((lane ^ m) << 2, __float_as_int(v))); }
; DEVINL void phase_gemm_res(const Params& p, const u16* A, int lda, const u16* B, int K, const float* resid, char* smem, int wv) {
;     ...
; #pragma unroll
;     for (int ai = 0; ai < 2; ++ai)
; #pragma unroll
;       for (int m = 0; m < 4; ++m) {
;         int row = m0 + ai * 128 + wr * 64 + m * 16 + fr;
;         size_t off = (size_t)row * DM + n0 + wc * 32 + fq * 4;
;         size_t offw = (size_t)row * DM + n0 + wc * 32 + (fq & 1) * 16 + (fq >> 1) * 8;
;         float ss = 0.f;
; #pragma unroll
;         for (int bj = 0; bj < 2; ++bj) {
;           f32x4 vv[2];
; #pragma unroll
;           for (int n = 0; n < 2; ++n) {
;             float4 rv = *(const float4*)(resid + off + bj * 128 + n * 16);
;             f32x4 v = acc[ai][bj][m][n];
;             v[0] += rv.x; v[1] += rv.y; v[2] += rv.z; v[3] += rv.w;
;             float4 ov; ov.x = v[0]; ov.y = v[1]; ov.z = v[2]; ov.w = v[3];
;             *(float4*)(out + off + bj * 128 + n * 16) = ov;
;             ss += sumsq4(v);
;             vv[n] = v;
;           }
;           *(u32x4*)(xb + offw + bj * 128) = widen2(vv[0], vv[1]);
;         }
;         ss += shx(ss, 16, lane); ss += shx(ss, 32, lane);
;         if (fq == 0) part[(size_t)row * 32 + pn * 4 + wc] = ss;
;       }
.LBB0_866:
	s_or_b64 exec, exec, s[30:31]
	v_add_u32_e32 v32, 0xa0, v130
	s_waitcnt lgkmcnt(0)
	v_ashrrev_i32_e32 v33, 31, v32
	v_lshlrev_b64 v[34:35], 11, v[32:33]
	v_lshl_add_u64 v[34:35], v[34:35], 0, s[24:25]
	v_or_b32_e32 v36, v34, v132
	v_mov_b32_e32 v37, v35
	v_readlane_b32 s40, v254, 2
	v_lshlrev_b64 v[36:37], 2, v[36:37]
	v_readlane_b32 s41, v254, 3
	v_lshl_add_u64 v[40:41], s[92:93], 0, v[36:37]
	v_lshl_add_u64 v[42:43], v[34:35], 1, v[124:125]
	v_lshl_add_u64 v[38:39], s[40:41], 0, v[36:37]
	global_load_dwordx4 v[200:203], v[38:39], off
	global_load_dwordx4 v[204:207], v[38:39], off offset:64
	global_load_dwordx4 v[208:211], v[38:39], off offset:512
	global_load_dwordx4 v[212:215], v[38:39], off offset:576
	v_readlane_b32 s42, v254, 4
	v_readlane_b32 s43, v254, 5
	v_readlane_b32 s44, v254, 6
	v_readlane_b32 s45, v254, 7
	v_readlane_b32 s46, v254, 8
	v_readlane_b32 s47, v254, 9
	v_readlane_b32 s48, v254, 10
	v_readlane_b32 s49, v254, 11
	v_readlane_b32 s50, v254, 12
	v_readlane_b32 s51, v254, 13
	v_readlane_b32 s52, v254, 14
	v_readlane_b32 s53, v254, 15
	v_readlane_b32 s54, v254, 16
	v_readlane_b32 s55, v254, 17
	s_waitcnt vmcnt(0)
	v_pk_add_f32 v[28:29], v[28:29], v[200:201]
	v_pk_add_f32 v[30:31], v[30:31], v[202:203]
	global_store_dwordx4 v[40:41], v[28:31], off
	v_pk_mul_f32 v[44:45], v[28:29], v[28:29]
	v_pk_mul_f32 v[46:47], v[30:31], v[30:31]
	v_cvt_pk_bf16_f32 v28, v28, v29
	v_cvt_pk_bf16_f32 v29, v30, v31
	v_pk_add_f32 v[24:25], v[24:25], v[204:205]
	v_pk_add_f32 v[26:27], v[26:27], v[206:207]
	v_cvt_pk_bf16_f32 v30, v24, v25
	v_cvt_pk_bf16_f32 v31, v26, v27
	s_nop 0
	v_permlane16_swap_b32_e32 v28, v30
	v_permlane16_swap_b32_e32 v29, v31
	global_store_dwordx4 v[40:41], v[24:27], off offset:64
	global_store_dwordx4 v[42:43], v[28:31], off
	v_pk_mul_f32 v[34:35], v[24:25], v[24:25]
	v_pk_mul_f32 v[36:37], v[26:27], v[26:27]
	v_add_f32_e32 v34, v34, v35
	v_add_f32_e32 v34, v36, v34
	v_add_f32_e32 v34, v37, v34
	v_pk_add_f32 v[20:21], v[20:21], v[208:209]
	v_pk_add_f32 v[22:23], v[22:23], v[210:211]
	global_store_dwordx4 v[40:41], v[20:23], off offset:512
	v_pk_mul_f32 v[28:29], v[20:21], v[20:21]
	v_add_f32_e32 v38, v44, v45
	v_pk_mul_f32 v[30:31], v[22:23], v[22:23]
	v_add_f32_e32 v38, v46, v38
	v_add_f32_e32 v28, v28, v29
	v_add_f32_e32 v38, v47, v38
	v_add_f32_e32 v28, v30, v28
	v_add_f32_e32 v34, v38, v34
	v_add_f32_e32 v28, v31, v28
	v_add_f32_e32 v28, v34, v28
	v_cvt_pk_bf16_f32 v20, v20, v21
	v_cvt_pk_bf16_f32 v21, v22, v23
	v_pk_add_f32 v[16:17], v[16:17], v[212:213]
	v_pk_add_f32 v[18:19], v[18:19], v[214:215]
	v_pk_mul_f32 v[24:25], v[16:17], v[16:17]
	v_pk_mul_f32 v[26:27], v[18:19], v[18:19]
	v_add_f32_e32 v24, v24, v25
	v_add_f32_e32 v24, v26, v24
	v_add_f32_e32 v24, v27, v24
	v_add_f32_e32 v24, v28, v24
	global_store_dwordx4 v[40:41], v[16:19], off offset:576
	v_cvt_pk_bf16_f32 v22, v16, v17
	ds_bpermute_b32 v16, v117, v24
	v_cvt_pk_bf16_f32 v23, v18, v19
	v_permlane16_swap_b32_e32 v20, v22
	s_nop 0
	v_permlane16_swap_b32_e32 v21, v23
	s_waitcnt lgkmcnt(0)
	v_add_f32_e32 v16, v24, v16
	ds_bpermute_b32 v17, v116, v16
	global_store_dwordx4 v[42:43], v[20:23], off offset:256
	s_and_saveexec_b64 s[30:31], vcc
	s_cbranch_execz .LBB0_868
	v_lshlrev_b64 v[18:19], 7, v[32:33]
	v_lshl_add_u64 v[18:19], s[28:29], 0, v[18:19]
	s_waitcnt lgkmcnt(0)
	v_add_f32_e32 v16, v16, v17
	global_store_dword v[18:19], v16, off
.LBB0_868:
	s_or_b64 exec, exec, s[30:31]
	v_add_u32_e32 v16, 0xb0, v130
	s_waitcnt lgkmcnt(0)
	v_ashrrev_i32_e32 v17, 31, v16
	v_lshlrev_b64 v[18:19], 11, v[16:17]
	v_lshl_add_u64 v[18:19], v[18:19], 0, s[24:25]
	v_or_b32_e32 v20, v18, v132
	v_mov_b32_e32 v21, v19
	v_readlane_b32 s40, v254, 2
	v_lshlrev_b64 v[20:21], 2, v[20:21]
	v_readlane_b32 s41, v254, 3
	v_lshl_add_u64 v[24:25], s[92:93], 0, v[20:21]
	v_lshl_add_u64 v[26:27], v[18:19], 1, v[124:125]
	v_lshl_add_u64 v[22:23], s[40:41], 0, v[20:21]
	global_load_dwordx4 v[200:203], v[22:23], off
	global_load_dwordx4 v[204:207], v[22:23], off offset:64
	global_load_dwordx4 v[208:211], v[22:23], off offset:512
	global_load_dwordx4 v[212:215], v[22:23], off offset:576
	v_readlane_b32 s42, v254, 4
	v_readlane_b32 s43, v254, 5
	v_readlane_b32 s44, v254, 6
	v_readlane_b32 s45, v254, 7
	v_readlane_b32 s46, v254, 8
	v_readlane_b32 s47, v254, 9
	v_readlane_b32 s48, v254, 10
	v_readlane_b32 s49, v254, 11
	v_readlane_b32 s50, v254, 12
	v_readlane_b32 s51, v254, 13
	v_readlane_b32 s52, v254, 14
	v_readlane_b32 s53, v254, 15
	v_readlane_b32 s54, v254, 16
	v_readlane_b32 s55, v254, 17
	s_waitcnt vmcnt(0)
	v_pk_add_f32 v[12:13], v[12:13], v[200:201]
	v_pk_add_f32 v[14:15], v[14:15], v[202:203]
	global_store_dwordx4 v[24:25], v[12:15], off
	v_pk_mul_f32 v[28:29], v[12:13], v[12:13]
	v_pk_mul_f32 v[30:31], v[14:15], v[14:15]
	v_cvt_pk_bf16_f32 v12, v12, v13
	v_cvt_pk_bf16_f32 v13, v14, v15
	v_pk_add_f32 v[8:9], v[8:9], v[204:205]
	v_pk_add_f32 v[10:11], v[10:11], v[206:207]
	v_cvt_pk_bf16_f32 v14, v8, v9
	v_cvt_pk_bf16_f32 v15, v10, v11
	s_nop 0
	v_permlane16_swap_b32_e32 v12, v14
	v_permlane16_swap_b32_e32 v13, v15
	global_store_dwordx4 v[24:25], v[8:11], off offset:64
	global_store_dwordx4 v[26:27], v[12:15], off
	v_pk_mul_f32 v[18:19], v[8:9], v[8:9]
	v_pk_mul_f32 v[20:21], v[10:11], v[10:11]
	v_add_f32_e32 v18, v18, v19
	v_add_f32_e32 v18, v20, v18
	v_add_f32_e32 v18, v21, v18
	v_pk_add_f32 v[4:5], v[4:5], v[208:209]
	v_pk_add_f32 v[6:7], v[6:7], v[210:211]
	global_store_dwordx4 v[24:25], v[4:7], off offset:512
	v_pk_mul_f32 v[12:13], v[4:5], v[4:5]
	v_add_f32_e32 v22, v28, v29
	v_pk_mul_f32 v[14:15], v[6:7], v[6:7]
	v_add_f32_e32 v22, v30, v22
	v_add_f32_e32 v12, v12, v13
	v_add_f32_e32 v22, v31, v22
	v_add_f32_e32 v12, v14, v12
	v_add_f32_e32 v18, v22, v18
	v_add_f32_e32 v12, v15, v12
	v_add_f32_e32 v12, v18, v12
	v_cvt_pk_bf16_f32 v4, v4, v5
	v_cvt_pk_bf16_f32 v5, v6, v7
	v_pk_add_f32 v[0:1], v[0:1], v[212:213]
	v_pk_add_f32 v[2:3], v[2:3], v[214:215]
	v_pk_mul_f32 v[8:9], v[0:1], v[0:1]
	v_pk_mul_f32 v[10:11], v[2:3], v[2:3]
	v_add_f32_e32 v8, v8, v9
	v_add_f32_e32 v8, v10, v8
	v_add_f32_e32 v8, v11, v8
	v_add_f32_e32 v8, v12, v8
	global_store_dwordx4 v[24:25], v[0:3], off offset:576
	v_cvt_pk_bf16_f32 v6, v0, v1
	ds_bpermute_b32 v0, v117, v8
	v_cvt_pk_bf16_f32 v7, v2, v3
	v_permlane16_swap_b32_e32 v4, v6
	s_nop 0
	v_permlane16_swap_b32_e32 v5, v7
	s_waitcnt lgkmcnt(0)
	v_add_f32_e32 v0, v8, v0
	ds_bpermute_b32 v1, v116, v0
	global_store_dwordx4 v[26:27], v[4:7], off offset:256
	s_and_saveexec_b64 s[24:25], vcc
	s_cbranch_execz .LBB0_845
	v_lshlrev_b64 v[2:3], 7, v[16:17]
	v_lshl_add_u64 v[2:3], s[28:29], 0, v[2:3]
	s_waitcnt lgkmcnt(0)
	v_add_f32_e32 v0, v0, v1
	global_store_dword v[2:3], v0, off
	s_branch .LBB0_845

; DEVINL int opaque_tid(int wv) { int t = (wv << 6) | (int)__builtin_amdgcn_mbcnt_hi(~0u, __builtin_amdgcn_mbcnt_lo(~0u, 0u)); asm volatile("" : "+v"(t)); return t; }
; DEVINL float shx(float v, int m, int lane) { return __int_as_float(__builtin_amdgcn_ds_bpermute((lane ^ m) << 2, __float_as_int(v))); }
; DEVINL void phase_gemm_res(const Params& p, const u16* A, int lda, const u16* B, int K, const float* resid, char* smem, int wv) {
;     ...
;   for (int tile = blockIdx.x; tile < NT * MT; tile += gridDim.x) {
;     const int tid = opaque_tid(wv), lane = tid & 63, wid = __builtin_amdgcn_readfirstlane(tid >> 6), wr = wid >> 2, wc = wid & 3, fr = lane & 15, fq = lane >> 4;
;     int pm, pn; tile_map(tile, MT, NT, pm, pn);
;     const int m0 = pm * 256, n0 = pn * 256;
;     f32x4 acc[2][2][4][2];
;     gemm8_mainloop(A, lda, B, K, K, m0, n0, acc, smem, tid);
;     if (tile + (int)gridDim.x < NT * MT) { int pm2, pn2; tile_map(tile + gridDim.x, MT, NT, pm2, pn2); gemm8_issue(A, lda, B, K, pm2 * 256, pn2 * 256, smem, tid); }
; #pragma unroll
;     for (int ai = 0; ai < 2; ++ai)
; #pragma unroll
;       for (int m = 0; m < 4; ++m) {
;         int row = m0 + ai * 128 + wr * 64 + m * 16 + fr;
;         size_t off = (size_t)row * DM + n0 + wc * 32 + fq * 4;
;         size_t offw = (size_t)row * DM + n0 + wc * 32 + (fq & 1) * 16 + (fq >> 1) * 8;
;         float ss = 0.f;
; #pragma unroll
;         for (int bj = 0; bj < 2; ++bj) {
;           f32x4 vv[2];
; #pragma unroll
;           for (int n = 0; n < 2; ++n) {
;             float4 rv = *(const float4*)(resid + off + bj * 128 + n * 16);
;             f32x4 v = acc[ai][bj][m][n];
;             v[0] += rv.x; v[1] += rv.y; v[2] += rv.z; v[3] += rv.w;
;             float4 ov; ov.x = v[0]; ov.y = v[1]; ov.z = v[2]; ov.w = v[3];
;             *(float4*)(out + off + bj * 128 + n * 16) = ov;
;             ss += sumsq4(v);
;             vv[n] = v;
;           }
;           *(u32x4*)(xb + offw + bj * 128) = widen2(vv[0], vv[1]);
;         }
;         ss += shx(ss, 16, lane); ss += shx(ss, 32, lane);
;         if (fq == 0) part[(size_t)row * 32 + pn * 4 + wc] = ss;
;       }
.LBB0_970:
	s_ashr_i32 s0, s29, 2
	s_andn2_b32 s0, s0, 63
	v_or_b32_e32 v128, s0, v128
	s_bfe_u32 s27, s29, 0x20006
	v_add_u32_e32 v130, s26, v128
	v_lshrrev_b32_e32 v128, 2, v151
	v_and_b32_e32 v131, 16, v151
	s_lshl_b32 s0, s27, 5
	v_and_b32_e32 v136, 12, v128
	v_and_or_b32 v128, v128, 8, v131
	v_ashrrev_i32_e32 v131, 31, v130
	s_or_b32 s22, s22, s0
	v_lshlrev_b64 v[134:135], 11, v[130:131]
	v_lshlrev_b32_e32 v128, 1, v128
	v_lshl_add_u64 v[142:143], v[134:135], 0, s[22:23]
	v_lshl_add_u64 v[132:133], s[90:91], 0, v[128:129]
	v_lshl_add_u64 v[134:135], v[142:143], 2, s[92:93]
	v_lshlrev_b32_e32 v128, 2, v136
	v_lshl_add_u64 v[146:147], v[134:135], 0, v[128:129]
	global_load_dwordx4 v[200:203], v[146:147], off
	global_load_dwordx4 v[204:207], v[146:147], off offset:64
	global_load_dwordx4 v[208:211], v[146:147], off offset:512
	global_load_dwordx4 v[212:215], v[146:147], off offset:576
	v_lshl_add_u64 v[148:149], v[142:143], 1, v[132:133]
	s_lshl_b32 s0, s28, 2
	s_ashr_i32 s1, s0, 31
	s_lshl_b64 s[0:1], s[0:1], 2
	s_add_u32 s0, s60, s0
	s_addc_u32 s1, s61, s1
	s_lshl_b32 s26, s27, 2
	s_add_u32 s26, s0, s26
	s_addc_u32 s27, s1, 0
	s_waitcnt vmcnt(0)
	v_pk_add_f32 v[124:125], v[124:125], v[200:201]
	v_pk_add_f32 v[126:127], v[126:127], v[202:203]
	v_pk_add_f32 v[134:135], v[120:121], v[204:205]
	v_pk_add_f32 v[136:137], v[122:123], v[206:207]
	v_cvt_pk_bf16_f32 v120, v124, v125
	v_cvt_pk_bf16_f32 v121, v126, v127
	v_cvt_pk_bf16_f32 v122, v134, v135
	v_cvt_pk_bf16_f32 v123, v136, v137
	s_nop 0
	v_permlane16_swap_b32_e32 v120, v122
	v_permlane16_swap_b32_e32 v121, v123
	global_store_dwordx4 v[146:147], v[124:127], off
	global_store_dwordx4 v[146:147], v[134:137], off offset:64
	global_store_dwordx4 v[148:149], v[120:123], off
	s_nop 1
	v_and_b32_e32 v120, 63, v151
	v_lshlrev_b32_e32 v122, 2, v120
	v_cmp_gt_u32_e32 vcc, 16, v120
	v_xor_b32_e32 v121, 64, v122
	v_xor_b32_e32 v120, 0x80, v122
	v_pk_mul_f32 v[122:123], v[124:125], v[124:125]
	v_pk_mul_f32 v[124:125], v[126:127], v[126:127]
	v_pk_mul_f32 v[126:127], v[134:135], v[134:135]
	v_pk_mul_f32 v[134:135], v[136:137], v[136:137]
	v_add_f32_e32 v126, v126, v127
	v_add_f32_e32 v122, v122, v123
	v_add_f32_e32 v123, v134, v126
	v_add_f32_e32 v122, v124, v122
	v_add_f32_e32 v123, v135, v123
	v_add_f32_e32 v122, v125, v122
	v_add_f32_e32 v136, v122, v123
	v_pk_add_f32 v[112:113], v[112:113], v[208:209]
	v_pk_add_f32 v[114:115], v[114:115], v[210:211]
	v_pk_add_f32 v[116:117], v[116:117], v[212:213]
	v_pk_mul_f32 v[122:123], v[112:113], v[112:113]
	v_pk_add_f32 v[118:119], v[118:119], v[214:215]
	v_pk_mul_f32 v[124:125], v[114:115], v[114:115]
	v_pk_mul_f32 v[126:127], v[116:117], v[116:117]
	v_add_f32_e32 v122, v122, v123
	v_pk_mul_f32 v[134:135], v[118:119], v[118:119]
	v_add_f32_e32 v123, v126, v127
	v_add_f32_e32 v122, v124, v122
	v_add_f32_e32 v123, v134, v123
	v_add_f32_e32 v122, v125, v122
	v_add_f32_e32 v123, v135, v123
	v_add_f32_e32 v122, v136, v122
	v_add_f32_e32 v126, v122, v123
	ds_bpermute_b32 v127, v121, v126
	global_store_dwordx4 v[146:147], v[112:115], off offset:512
	v_cvt_pk_bf16_f32 v122, v112, v113
	v_cvt_pk_bf16_f32 v123, v114, v115
	v_cvt_pk_bf16_f32 v124, v116, v117
	s_waitcnt lgkmcnt(0)
	v_add_f32_e32 v112, v126, v127
	ds_bpermute_b32 v113, v120, v112
	v_cvt_pk_bf16_f32 v125, v118, v119
	v_permlane16_swap_b32_e32 v122, v124
	s_nop 0
	v_permlane16_swap_b32_e32 v123, v125
	global_store_dwordx4 v[146:147], v[116:119], off offset:576
	global_store_dwordx4 v[148:149], v[122:125], off offset:256
	s_and_saveexec_b64 s[28:29], vcc
	s_cbranch_execz .LBB0_972
	v_lshlrev_b64 v[114:115], 7, v[130:131]
	v_lshl_add_u64 v[114:115], s[26:27], 0, v[114:115]
	s_waitcnt lgkmcnt(0)
	v_add_f32_e32 v112, v112, v113
	global_store_dword v[114:115], v112, off
.LBB0_972:
	s_or_b64 exec, exec, s[28:29]
	v_or_b32_e32 v112, 16, v130
	s_waitcnt lgkmcnt(0)
	v_ashrrev_i32_e32 v113, 31, v112
	v_lshlrev_b64 v[114:115], 11, v[112:113]
	v_lshl_add_u64 v[118:119], v[114:115], 0, s[22:23]
	v_lshl_add_u64 v[114:115], v[118:119], 2, s[92:93]
	v_lshl_add_u64 v[126:127], v[114:115], 0, v[128:129]
	global_load_dwordx4 v[200:203], v[126:127], off
	global_load_dwordx4 v[204:207], v[126:127], off offset:64
	global_load_dwordx4 v[208:211], v[126:127], off offset:512
	global_load_dwordx4 v[212:215], v[126:127], off offset:576
	v_lshl_add_u64 v[118:119], v[118:119], 1, v[132:133]
	s_waitcnt vmcnt(0)
	v_pk_add_f32 v[108:109], v[108:109], v[200:201]
	v_pk_add_f32 v[110:111], v[110:111], v[202:203]
	v_pk_add_f32 v[104:105], v[104:105], v[204:205]
	v_pk_add_f32 v[106:107], v[106:107], v[206:207]
	v_cvt_pk_bf16_f32 v114, v108, v109
	v_cvt_pk_bf16_f32 v115, v110, v111
	v_cvt_pk_bf16_f32 v116, v104, v105
	v_cvt_pk_bf16_f32 v117, v106, v107
	s_nop 0
	v_permlane16_swap_b32_e32 v114, v116
	v_permlane16_swap_b32_e32 v115, v117
	global_store_dwordx4 v[126:127], v[108:111], off
	global_store_dwordx4 v[126:127], v[104:107], off offset:64
	global_store_dwordx4 v[118:119], v[114:117], off
	s_nop 0
	v_pk_mul_f32 v[108:109], v[108:109], v[108:109]
	v_pk_mul_f32 v[104:105], v[104:105], v[104:105]
	v_pk_mul_f32 v[110:111], v[110:111], v[110:111]
	v_pk_mul_f32 v[106:107], v[106:107], v[106:107]
	v_add_f32_e32 v104, v104, v105
	v_add_f32_e32 v105, v108, v109
	v_add_f32_e32 v104, v106, v104
	v_add_f32_e32 v105, v110, v105
	v_add_f32_e32 v104, v107, v104
	v_add_f32_e32 v105, v111, v105
	v_add_f32_e32 v131, v105, v104
	v_pk_add_f32 v[96:97], v[96:97], v[208:209]
	v_pk_add_f32 v[98:99], v[98:99], v[210:211]
	v_pk_add_f32 v[100:101], v[100:101], v[212:213]
	v_pk_mul_f32 v[104:105], v[96:97], v[96:97]
	v_pk_add_f32 v[102:103], v[102:103], v[214:215]
	v_pk_mul_f32 v[106:107], v[98:99], v[98:99]
	v_pk_mul_f32 v[108:109], v[100:101], v[100:101]
	v_add_f32_e32 v104, v104, v105
	v_pk_mul_f32 v[110:111], v[102:103], v[102:103]
	v_add_f32_e32 v105, v108, v109
	v_add_f32_e32 v104, v106, v104
	v_add_f32_e32 v105, v110, v105
	v_add_f32_e32 v104, v107, v104
	v_add_f32_e32 v105, v111, v105
	v_add_f32_e32 v104, v131, v104
	v_add_f32_e32 v108, v104, v105
	ds_bpermute_b32 v109, v121, v108
	global_store_dwordx4 v[126:127], v[96:99], off offset:512
	v_cvt_pk_bf16_f32 v104, v96, v97
	v_cvt_pk_bf16_f32 v105, v98, v99
	v_cvt_pk_bf16_f32 v106, v100, v101
	s_waitcnt lgkmcnt(0)
	v_add_f32_e32 v96, v108, v109
	ds_bpermute_b32 v97, v120, v96
	v_cvt_pk_bf16_f32 v107, v102, v103
	v_permlane16_swap_b32_e32 v104, v106
	s_nop 0
	v_permlane16_swap_b32_e32 v105, v107
	global_store_dwordx4 v[126:127], v[100:103], off offset:576
	global_store_dwordx4 v[118:119], v[104:107], off offset:256
	s_and_saveexec_b64 s[28:29], vcc
	s_cbranch_execz .LBB0_974
	v_lshlrev_b64 v[98:99], 7, v[112:113]
	v_lshl_add_u64 v[98:99], s[26:27], 0, v[98:99]
	s_waitcnt lgkmcnt(0)
	v_add_f32_e32 v96, v96, v97
	global_store_dword v[98:99], v96, off
; DEVINL float shx(float v, int m, int lane) { return __int_as_float(__builtin_amdgcn_ds_bpermute((lane ^ m) << 2, __float_as_int(v))); }
; DEVINL void phase_gemm_res(const Params& p, const u16* A, int lda, const u16* B, int K, const float* resid, char* smem, int wv) {
;     ...
; #pragma unroll
;     for (int ai = 0; ai < 2; ++ai)
; #pragma unroll
;       for (int m = 0; m < 4; ++m) {
;         int row = m0 + ai * 128 + wr * 64 + m * 16 + fr;
;         size_t off = (size_t)row * DM + n0 + wc * 32 + fq * 4;
;         size_t offw = (size_t)row * DM + n0 + wc * 32 + (fq & 1) * 16 + (fq >> 1) * 8;
;         float ss = 0.f;
; #pragma unroll
;         for (int bj = 0; bj < 2; ++bj) {
;           f32x4 vv[2];
; #pragma unroll
;           for (int n = 0; n < 2; ++n) {
;             float4 rv = *(const float4*)(resid + off + bj * 128 + n * 16);
;             f32x4 v = acc[ai][bj][m][n];
;             v[0] += rv.x; v[1] += rv.y; v[2] += rv.z; v[3] += rv.w;
;             float4 ov; ov.x = v[0]; ov.y = v[1]; ov.z = v[2]; ov.w = v[3];
;             *(float4*)(out + off + bj * 128 + n * 16) = ov;
;             ss += sumsq4(v);
;             vv[n] = v;
;           }
;           *(u32x4*)(xb + offw + bj * 128) = widen2(vv[0], vv[1]);
;         }
;         ss += shx(ss, 16, lane); ss += shx(ss, 32, lane);
;         if (fq == 0) part[(size_t)row * 32 + pn * 4 + wc] = ss;
;       }
.LBB0_974:
	s_or_b64 exec, exec, s[28:29]
	v_or_b32_e32 v96, 32, v130
	s_waitcnt lgkmcnt(0)
	v_ashrrev_i32_e32 v97, 31, v96
	v_lshlrev_b64 v[98:99], 11, v[96:97]
	v_lshl_add_u64 v[106:107], v[98:99], 0, s[22:23]
	v_lshl_add_u64 v[98:99], v[106:107], 2, s[92:93]
	v_lshl_add_u64 v[108:109], v[98:99], 0, v[128:129]
	global_load_dwordx4 v[200:203], v[108:109], off
	global_load_dwordx4 v[204:207], v[108:109], off offset:64
	global_load_dwordx4 v[208:211], v[108:109], off offset:512
	global_load_dwordx4 v[212:215], v[108:109], off offset:576
	v_lshl_add_u64 v[106:107], v[106:107], 1, v[132:133]
	s_waitcnt vmcnt(0)
	v_pk_add_f32 v[92:93], v[92:93], v[200:201]
	v_pk_add_f32 v[94:95], v[94:95], v[202:203]
	v_pk_add_f32 v[88:89], v[88:89], v[204:205]
	v_pk_add_f32 v[90:91], v[90:91], v[206:207]
	v_cvt_pk_bf16_f32 v98, v92, v93
	v_cvt_pk_bf16_f32 v99, v94, v95
	v_cvt_pk_bf16_f32 v100, v88, v89
	v_cvt_pk_bf16_f32 v101, v90, v91
	s_nop 0
	v_permlane16_swap_b32_e32 v98, v100
	v_permlane16_swap_b32_e32 v99, v101
	global_store_dwordx4 v[108:109], v[92:95], off
	global_store_dwordx4 v[108:109], v[88:91], off offset:64
	global_store_dwordx4 v[106:107], v[98:101], off
	s_nop 0
	v_pk_mul_f32 v[92:93], v[92:93], v[92:93]
	v_pk_mul_f32 v[88:89], v[88:89], v[88:89]
	v_pk_mul_f32 v[94:95], v[94:95], v[94:95]
	v_pk_mul_f32 v[90:91], v[90:91], v[90:91]
	v_add_f32_e32 v88, v88, v89
	v_add_f32_e32 v89, v92, v93
	v_add_f32_e32 v88, v90, v88
	v_add_f32_e32 v89, v94, v89
	v_add_f32_e32 v88, v91, v88
	v_add_f32_e32 v89, v95, v89
	v_add_f32_e32 v110, v89, v88
	v_pk_add_f32 v[80:81], v[80:81], v[208:209]
	v_pk_add_f32 v[82:83], v[82:83], v[210:211]
	v_pk_add_f32 v[84:85], v[84:85], v[212:213]
	v_pk_mul_f32 v[88:89], v[80:81], v[80:81]
	v_pk_add_f32 v[86:87], v[86:87], v[214:215]
	v_pk_mul_f32 v[90:91], v[82:83], v[82:83]
	v_pk_mul_f32 v[92:93], v[84:85], v[84:85]
	v_add_f32_e32 v88, v88, v89
	v_pk_mul_f32 v[94:95], v[86:87], v[86:87]
	v_add_f32_e32 v89, v92, v93
	v_add_f32_e32 v88, v90, v88
	v_add_f32_e32 v89, v94, v89
	v_add_f32_e32 v88, v91, v88
	v_add_f32_e32 v89, v95, v89
	v_add_f32_e32 v88, v110, v88
	v_add_f32_e32 v92, v88, v89
	ds_bpermute_b32 v93, v121, v92
	global_store_dwordx4 v[108:109], v[80:83], off offset:512
	v_cvt_pk_bf16_f32 v88, v80, v81
	v_cvt_pk_bf16_f32 v89, v82, v83
	v_cvt_pk_bf16_f32 v90, v84, v85
	s_waitcnt lgkmcnt(0)
	v_add_f32_e32 v80, v92, v93
	ds_bpermute_b32 v81, v120, v80
	v_cvt_pk_bf16_f32 v91, v86, v87
	v_permlane16_swap_b32_e32 v88, v90
	s_nop 0
	v_permlane16_swap_b32_e32 v89, v91
	global_store_dwordx4 v[108:109], v[84:87], off offset:576
	global_store_dwordx4 v[106:107], v[88:91], off offset:256
	s_and_saveexec_b64 s[28:29], vcc
	s_cbranch_execz .LBB0_976
	v_lshlrev_b64 v[82:83], 7, v[96:97]
	v_lshl_add_u64 v[82:83], s[26:27], 0, v[82:83]
	s_waitcnt lgkmcnt(0)
	v_add_f32_e32 v80, v80, v81
	global_store_dword v[82:83], v80, off
.LBB0_976:
	s_or_b64 exec, exec, s[28:29]
	v_or_b32_e32 v80, 48, v130
	s_waitcnt lgkmcnt(0)
	v_ashrrev_i32_e32 v81, 31, v80
	v_lshlrev_b64 v[82:83], 11, v[80:81]
	v_lshl_add_u64 v[90:91], v[82:83], 0, s[22:23]
	v_lshl_add_u64 v[82:83], v[90:91], 2, s[92:93]
	v_lshl_add_u64 v[92:93], v[82:83], 0, v[128:129]
	global_load_dwordx4 v[200:203], v[92:93], off
	global_load_dwordx4 v[204:207], v[92:93], off offset:64
	global_load_dwordx4 v[208:211], v[92:93], off offset:512
	global_load_dwordx4 v[212:215], v[92:93], off offset:576
	v_lshl_add_u64 v[90:91], v[90:91], 1, v[132:133]
	s_waitcnt vmcnt(0)
	v_pk_add_f32 v[76:77], v[76:77], v[200:201]
	v_pk_add_f32 v[78:79], v[78:79], v[202:203]
	v_pk_add_f32 v[72:73], v[72:73], v[204:205]
	v_pk_add_f32 v[74:75], v[74:75], v[206:207]
	v_cvt_pk_bf16_f32 v82, v76, v77
	v_cvt_pk_bf16_f32 v83, v78, v79
	v_cvt_pk_bf16_f32 v84, v72, v73
	v_cvt_pk_bf16_f32 v85, v74, v75
	s_nop 0
	v_permlane16_swap_b32_e32 v82, v84
	v_permlane16_swap_b32_e32 v83, v85
	global_store_dwordx4 v[92:93], v[76:79], off
	global_store_dwordx4 v[92:93], v[72:75], off offset:64
	global_store_dwordx4 v[90:91], v[82:85], off
	s_nop 0
	v_pk_mul_f32 v[76:77], v[76:77], v[76:77]
	v_pk_mul_f32 v[72:73], v[72:73], v[72:73]
	v_pk_mul_f32 v[78:79], v[78:79], v[78:79]
	v_pk_mul_f32 v[74:75], v[74:75], v[74:75]
	v_add_f32_e32 v72, v72, v73
	v_add_f32_e32 v73, v76, v77
	v_add_f32_e32 v72, v74, v72
	v_add_f32_e32 v73, v78, v73
	v_add_f32_e32 v72, v75, v72
	v_add_f32_e32 v73, v79, v73
	v_add_f32_e32 v94, v73, v72
	v_pk_add_f32 v[64:65], v[64:65], v[208:209]
	v_pk_add_f32 v[66:67], v[66:67], v[210:211]
	v_pk_add_f32 v[68:69], v[68:69], v[212:213]
	v_pk_mul_f32 v[72:73], v[64:65], v[64:65]
	v_pk_add_f32 v[70:71], v[70:71], v[214:215]
	v_pk_mul_f32 v[74:75], v[66:67], v[66:67]
	v_pk_mul_f32 v[76:77], v[68:69], v[68:69]
	v_add_f32_e32 v72, v72, v73
	v_pk_mul_f32 v[78:79], v[70:71], v[70:71]
	v_add_f32_e32 v73, v76, v77
	v_add_f32_e32 v72, v74, v72
	v_add_f32_e32 v73, v78, v73
	v_add_f32_e32 v72, v75, v72
	v_add_f32_e32 v73, v79, v73
	v_add_f32_e32 v72, v94, v72
	v_add_f32_e32 v76, v72, v73
	ds_bpermute_b32 v77, v121, v76
	global_store_dwordx4 v[92:93], v[64:67], off offset:512
	v_cvt_pk_bf16_f32 v72, v64, v65
	v_cvt_pk_bf16_f32 v73, v66, v67
	v_cvt_pk_bf16_f32 v74, v68, v69
	s_waitcnt lgkmcnt(0)
	v_add_f32_e32 v64, v76, v77
	ds_bpermute_b32 v65, v120, v64
	v_cvt_pk_bf16_f32 v75, v70, v71
	v_permlane16_swap_b32_e32 v72, v74
	s_nop 0
	v_permlane16_swap_b32_e32 v73, v75
	global_store_dwordx4 v[92:93], v[68:71], off offset:576
	global_store_dwordx4 v[90:91], v[72:75], off offset:256
	s_and_saveexec_b64 s[28:29], vcc
	s_cbranch_execz .LBB0_978
	v_lshlrev_b64 v[66:67], 7, v[80:81]
	v_lshl_add_u64 v[66:67], s[26:27], 0, v[66:67]
	s_waitcnt lgkmcnt(0)
	v_add_f32_e32 v64, v64, v65
	global_store_dword v[66:67], v64, off
; DEVINL float shx(float v, int m, int lane) { return __int_as_float(__builtin_amdgcn_ds_bpermute((lane ^ m) << 2, __float_as_int(v))); }
; DEVINL void phase_gemm_res(const Params& p, const u16* A, int lda, const u16* B, int K, const float* resid, char* smem, int wv) {
;     ...
; #pragma unroll
;     for (int ai = 0; ai < 2; ++ai)
; #pragma unroll
;       for (int m = 0; m < 4; ++m) {
;         int row = m0 + ai * 128 + wr * 64 + m * 16 + fr;
;         size_t off = (size_t)row * DM + n0 + wc * 32 + fq * 4;
;         size_t offw = (size_t)row * DM + n0 + wc * 32 + (fq & 1) * 16 + (fq >> 1) * 8;
;         float ss = 0.f;
; #pragma unroll
;         for (int bj = 0; bj < 2; ++bj) {
;           f32x4 vv[2];
; #pragma unroll
;           for (int n = 0; n < 2; ++n) {
;             float4 rv = *(const float4*)(resid + off + bj * 128 + n * 16);
;             f32x4 v = acc[ai][bj][m][n];
;             v[0] += rv.x; v[1] += rv.y; v[2] += rv.z; v[3] += rv.w;
;             float4 ov; ov.x = v[0]; ov.y = v[1]; ov.z = v[2]; ov.w = v[3];
;             *(float4*)(out + off + bj * 128 + n * 16) = ov;
;             ss += sumsq4(v);
;             vv[n] = v;
;           }
;           *(u32x4*)(xb + offw + bj * 128) = widen2(vv[0], vv[1]);
;         }
;         ss += shx(ss, 16, lane); ss += shx(ss, 32, lane);
;         if (fq == 0) part[(size_t)row * 32 + pn * 4 + wc] = ss;
;       }
.LBB0_978:
	s_or_b64 exec, exec, s[28:29]
	v_add_u32_e32 v64, 0x80, v130
	s_waitcnt lgkmcnt(0)
	v_ashrrev_i32_e32 v65, 31, v64
	v_lshlrev_b64 v[66:67], 11, v[64:65]
	v_lshl_add_u64 v[74:75], v[66:67], 0, s[22:23]
	v_lshl_add_u64 v[66:67], v[74:75], 2, s[92:93]
	v_lshl_add_u64 v[76:77], v[66:67], 0, v[128:129]
	global_load_dwordx4 v[200:203], v[76:77], off
	global_load_dwordx4 v[204:207], v[76:77], off offset:64
	global_load_dwordx4 v[208:211], v[76:77], off offset:512
	global_load_dwordx4 v[212:215], v[76:77], off offset:576
	v_lshl_add_u64 v[74:75], v[74:75], 1, v[132:133]
	s_waitcnt vmcnt(0)
	v_pk_add_f32 v[60:61], v[60:61], v[200:201]
	v_pk_add_f32 v[62:63], v[62:63], v[202:203]
	v_pk_add_f32 v[56:57], v[56:57], v[204:205]
	v_pk_add_f32 v[58:59], v[58:59], v[206:207]
	v_cvt_pk_bf16_f32 v66, v60, v61
	v_cvt_pk_bf16_f32 v67, v62, v63
	v_cvt_pk_bf16_f32 v68, v56, v57
	v_cvt_pk_bf16_f32 v69, v58, v59
	s_nop 0
	v_permlane16_swap_b32_e32 v66, v68
	v_permlane16_swap_b32_e32 v67, v69
	global_store_dwordx4 v[76:77], v[60:63], off
	global_store_dwordx4 v[76:77], v[56:59], off offset:64
	global_store_dwordx4 v[74:75], v[66:69], off
	s_nop 0
	v_pk_mul_f32 v[60:61], v[60:61], v[60:61]
	v_pk_mul_f32 v[56:57], v[56:57], v[56:57]
	v_pk_mul_f32 v[62:63], v[62:63], v[62:63]
	v_pk_mul_f32 v[58:59], v[58:59], v[58:59]
	v_add_f32_e32 v56, v56, v57
	v_add_f32_e32 v57, v60, v61
	v_add_f32_e32 v56, v58, v56
	v_add_f32_e32 v57, v62, v57
	v_add_f32_e32 v56, v59, v56
	v_add_f32_e32 v57, v63, v57
	v_add_f32_e32 v78, v57, v56
	v_pk_add_f32 v[48:49], v[48:49], v[208:209]
	v_pk_add_f32 v[50:51], v[50:51], v[210:211]
	v_pk_add_f32 v[52:53], v[52:53], v[212:213]
	v_pk_mul_f32 v[56:57], v[48:49], v[48:49]
	v_pk_add_f32 v[54:55], v[54:55], v[214:215]
	v_pk_mul_f32 v[58:59], v[50:51], v[50:51]
	v_pk_mul_f32 v[60:61], v[52:53], v[52:53]
	v_add_f32_e32 v56, v56, v57
	v_pk_mul_f32 v[62:63], v[54:55], v[54:55]
	v_add_f32_e32 v57, v60, v61
	v_add_f32_e32 v56, v58, v56
	v_add_f32_e32 v57, v62, v57
	v_add_f32_e32 v56, v59, v56
	v_add_f32_e32 v57, v63, v57
	v_add_f32_e32 v56, v78, v56
	v_add_f32_e32 v60, v56, v57
	ds_bpermute_b32 v61, v121, v60
	global_store_dwordx4 v[76:77], v[48:51], off offset:512
	v_cvt_pk_bf16_f32 v56, v48, v49
	v_cvt_pk_bf16_f32 v57, v50, v51
	v_cvt_pk_bf16_f32 v58, v52, v53
	s_waitcnt lgkmcnt(0)
	v_add_f32_e32 v48, v60, v61
	ds_bpermute_b32 v49, v120, v48
	v_cvt_pk_bf16_f32 v59, v54, v55
	v_permlane16_swap_b32_e32 v56, v58
	s_nop 0
	v_permlane16_swap_b32_e32 v57, v59
	global_store_dwordx4 v[76:77], v[52:55], off offset:576
	global_store_dwordx4 v[74:75], v[56:59], off offset:256
	s_and_saveexec_b64 s[28:29], vcc
	s_cbranch_execz .LBB0_980
	v_lshlrev_b64 v[50:51], 7, v[64:65]
	v_lshl_add_u64 v[50:51], s[26:27], 0, v[50:51]
	s_waitcnt lgkmcnt(0)
	v_add_f32_e32 v48, v48, v49
	global_store_dword v[50:51], v48, off
.LBB0_980:
	s_or_b64 exec, exec, s[28:29]
	v_add_u32_e32 v48, 0x90, v130
	s_waitcnt lgkmcnt(0)
	v_ashrrev_i32_e32 v49, 31, v48
	v_lshlrev_b64 v[50:51], 11, v[48:49]
	v_lshl_add_u64 v[58:59], v[50:51], 0, s[22:23]
	v_lshl_add_u64 v[50:51], v[58:59], 2, s[92:93]
	v_lshl_add_u64 v[60:61], v[50:51], 0, v[128:129]
	global_load_dwordx4 v[200:203], v[60:61], off
	global_load_dwordx4 v[204:207], v[60:61], off offset:64
	global_load_dwordx4 v[208:211], v[60:61], off offset:512
	global_load_dwordx4 v[212:215], v[60:61], off offset:576
	v_lshl_add_u64 v[58:59], v[58:59], 1, v[132:133]
	s_waitcnt vmcnt(0)
	v_pk_add_f32 v[44:45], v[44:45], v[200:201]
	v_pk_add_f32 v[46:47], v[46:47], v[202:203]
	v_pk_add_f32 v[40:41], v[40:41], v[204:205]
	v_pk_add_f32 v[42:43], v[42:43], v[206:207]
	v_cvt_pk_bf16_f32 v50, v44, v45
	v_cvt_pk_bf16_f32 v51, v46, v47
	v_cvt_pk_bf16_f32 v52, v40, v41
	v_cvt_pk_bf16_f32 v53, v42, v43
	s_nop 0
	v_permlane16_swap_b32_e32 v50, v52
	v_permlane16_swap_b32_e32 v51, v53
	global_store_dwordx4 v[60:61], v[44:47], off
	global_store_dwordx4 v[60:61], v[40:43], off offset:64
	global_store_dwordx4 v[58:59], v[50:53], off
	s_nop 0
	v_pk_mul_f32 v[44:45], v[44:45], v[44:45]
	v_pk_mul_f32 v[40:41], v[40:41], v[40:41]
	v_pk_mul_f32 v[46:47], v[46:47], v[46:47]
	v_pk_mul_f32 v[42:43], v[42:43], v[42:43]
	v_add_f32_e32 v40, v40, v41
	v_add_f32_e32 v41, v44, v45
	v_add_f32_e32 v40, v42, v40
	v_add_f32_e32 v41, v46, v41
	v_add_f32_e32 v40, v43, v40
	v_add_f32_e32 v41, v47, v41
	v_add_f32_e32 v62, v41, v40
	v_pk_add_f32 v[32:33], v[32:33], v[208:209]
	v_pk_add_f32 v[34:35], v[34:35], v[210:211]
	v_pk_add_f32 v[36:37], v[36:37], v[212:213]
	v_pk_mul_f32 v[40:41], v[32:33], v[32:33]
	v_pk_add_f32 v[38:39], v[38:39], v[214:215]
	v_pk_mul_f32 v[42:43], v[34:35], v[34:35]
	v_pk_mul_f32 v[44:45], v[36:37], v[36:37]
	v_add_f32_e32 v40, v40, v41
	v_pk_mul_f32 v[46:47], v[38:39], v[38:39]
	v_add_f32_e32 v41, v44, v45
	v_add_f32_e32 v40, v42, v40
	v_add_f32_e32 v41, v46, v41
	v_add_f32_e32 v40, v43, v40
	v_add_f32_e32 v41, v47, v41
	v_add_f32_e32 v40, v62, v40
	v_add_f32_e32 v44, v40, v41
	ds_bpermute_b32 v45, v121, v44
	global_store_dwordx4 v[60:61], v[32:35], off offset:512
	v_cvt_pk_bf16_f32 v40, v32, v33
	v_cvt_pk_bf16_f32 v41, v34, v35
	v_cvt_pk_bf16_f32 v42, v36, v37
	s_waitcnt lgkmcnt(0)
	v_add_f32_e32 v32, v44, v45
	ds_bpermute_b32 v33, v120, v32
	v_cvt_pk_bf16_f32 v43, v38, v39
	v_permlane16_swap_b32_e32 v40, v42
	s_nop 0
	v_permlane16_swap_b32_e32 v41, v43
	global_store_dwordx4 v[60:61], v[36:39], off offset:576
	global_store_dwordx4 v[58:59], v[40:43], off offset:256
	s_and_saveexec_b64 s[28:29], vcc
	s_cbranch_execz .LBB0_982
	v_lshlrev_b64 v[34:35], 7, v[48:49]
	v_lshl_add_u64 v[34:35], s[26:27], 0, v[34:35]
	s_waitcnt lgkmcnt(0)
	v_add_f32_e32 v32, v32, v33
	global_store_dword v[34:35], v32, off
; DEVINL float shx(float v, int m, int lane) { return __int_as_float(__builtin_amdgcn_ds_bpermute((lane ^ m) << 2, __float_as_int(v))); }
; DEVINL void phase_gemm_res(const Params& p, const u16* A, int lda, const u16* B, int K, const float* resid, char* smem, int wv) {
;     ...
; #pragma unroll
;     for (int ai = 0; ai < 2; ++ai)
; #pragma unroll
;       for (int m = 0; m < 4; ++m) {
;         int row = m0 + ai * 128 + wr * 64 + m * 16 + fr;
;         size_t off = (size_t)row * DM + n0 + wc * 32 + fq * 4;
;         size_t offw = (size_t)row * DM + n0 + wc * 32 + (fq & 1) * 16 + (fq >> 1) * 8;
;         float ss = 0.f;
; #pragma unroll
;         for (int bj = 0; bj < 2; ++bj) {
;           f32x4 vv[2];
; #pragma unroll
;           for (int n = 0; n < 2; ++n) {
;             float4 rv = *(const float4*)(resid + off + bj * 128 + n * 16);
;             f32x4 v = acc[ai][bj][m][n];
;             v[0] += rv.x; v[1] += rv.y; v[2] += rv.z; v[3] += rv.w;
;             float4 ov; ov.x = v[0]; ov.y = v[1]; ov.z = v[2]; ov.w = v[3];
;             *(float4*)(out + off + bj * 128 + n * 16) = ov;
;             ss += sumsq4(v);
;             vv[n] = v;
;           }
;           *(u32x4*)(xb + offw + bj * 128) = widen2(vv[0], vv[1]);
;         }
;         ss += shx(ss, 16, lane); ss += shx(ss, 32, lane);
;         if (fq == 0) part[(size_t)row * 32 + pn * 4 + wc] = ss;
;       }
.LBB0_982:
	s_or_b64 exec, exec, s[28:29]
	v_add_u32_e32 v32, 0xa0, v130
	s_waitcnt lgkmcnt(0)
	v_ashrrev_i32_e32 v33, 31, v32
	v_lshlrev_b64 v[34:35], 11, v[32:33]
	v_lshl_add_u64 v[42:43], v[34:35], 0, s[22:23]
	v_lshl_add_u64 v[34:35], v[42:43], 2, s[92:93]
	v_lshl_add_u64 v[44:45], v[34:35], 0, v[128:129]
	global_load_dwordx4 v[200:203], v[44:45], off
	global_load_dwordx4 v[204:207], v[44:45], off offset:64
	global_load_dwordx4 v[208:211], v[44:45], off offset:512
	global_load_dwordx4 v[212:215], v[44:45], off offset:576
	v_lshl_add_u64 v[42:43], v[42:43], 1, v[132:133]
	s_waitcnt vmcnt(0)
	v_pk_add_f32 v[28:29], v[28:29], v[200:201]
	v_pk_add_f32 v[30:31], v[30:31], v[202:203]
	v_pk_add_f32 v[24:25], v[24:25], v[204:205]
	v_pk_add_f32 v[26:27], v[26:27], v[206:207]
	v_cvt_pk_bf16_f32 v34, v28, v29
	v_cvt_pk_bf16_f32 v35, v30, v31
	v_cvt_pk_bf16_f32 v36, v24, v25
	v_cvt_pk_bf16_f32 v37, v26, v27
	s_nop 0
	v_permlane16_swap_b32_e32 v34, v36
	v_permlane16_swap_b32_e32 v35, v37
	global_store_dwordx4 v[44:45], v[28:31], off
	global_store_dwordx4 v[44:45], v[24:27], off offset:64
	global_store_dwordx4 v[42:43], v[34:37], off
	s_nop 0
	v_pk_mul_f32 v[28:29], v[28:29], v[28:29]
	v_pk_mul_f32 v[24:25], v[24:25], v[24:25]
	v_pk_mul_f32 v[30:31], v[30:31], v[30:31]
	v_pk_mul_f32 v[26:27], v[26:27], v[26:27]
	v_add_f32_e32 v24, v24, v25
	v_add_f32_e32 v25, v28, v29
	v_add_f32_e32 v24, v26, v24
	v_add_f32_e32 v25, v30, v25
	v_add_f32_e32 v24, v27, v24
	v_add_f32_e32 v25, v31, v25
	v_add_f32_e32 v46, v25, v24
	v_pk_add_f32 v[16:17], v[16:17], v[208:209]
	v_pk_add_f32 v[18:19], v[18:19], v[210:211]
	v_pk_add_f32 v[20:21], v[20:21], v[212:213]
	v_pk_mul_f32 v[24:25], v[16:17], v[16:17]
	v_pk_add_f32 v[22:23], v[22:23], v[214:215]
	v_pk_mul_f32 v[26:27], v[18:19], v[18:19]
	v_pk_mul_f32 v[28:29], v[20:21], v[20:21]
	v_add_f32_e32 v24, v24, v25
	v_pk_mul_f32 v[30:31], v[22:23], v[22:23]
	v_add_f32_e32 v25, v28, v29
	v_add_f32_e32 v24, v26, v24
	v_add_f32_e32 v25, v30, v25
	v_add_f32_e32 v24, v27, v24
	v_add_f32_e32 v25, v31, v25
	v_add_f32_e32 v24, v46, v24
	v_add_f32_e32 v28, v24, v25
	ds_bpermute_b32 v29, v121, v28
	global_store_dwordx4 v[44:45], v[16:19], off offset:512
	v_cvt_pk_bf16_f32 v24, v16, v17
	v_cvt_pk_bf16_f32 v25, v18, v19
	v_cvt_pk_bf16_f32 v26, v20, v21
	s_waitcnt lgkmcnt(0)
	v_add_f32_e32 v16, v28, v29
	ds_bpermute_b32 v17, v120, v16
	v_cvt_pk_bf16_f32 v27, v22, v23
	v_permlane16_swap_b32_e32 v24, v26
	s_nop 0
	v_permlane16_swap_b32_e32 v25, v27
	global_store_dwordx4 v[44:45], v[20:23], off offset:576
	global_store_dwordx4 v[42:43], v[24:27], off offset:256
	s_and_saveexec_b64 s[28:29], vcc
	s_cbranch_execz .LBB0_984
	v_lshlrev_b64 v[18:19], 7, v[32:33]
	v_lshl_add_u64 v[18:19], s[26:27], 0, v[18:19]
	s_waitcnt lgkmcnt(0)
	v_add_f32_e32 v16, v16, v17
	global_store_dword v[18:19], v16, off
.LBB0_984:
	s_or_b64 exec, exec, s[28:29]
	v_add_u32_e32 v16, 0xb0, v130
	s_waitcnt lgkmcnt(0)
	v_ashrrev_i32_e32 v17, 31, v16
	v_lshlrev_b64 v[18:19], 11, v[16:17]
	v_lshl_add_u64 v[18:19], v[18:19], 0, s[22:23]
	v_lshl_add_u64 v[20:21], v[18:19], 2, s[92:93]
	v_lshl_add_u64 v[24:25], v[20:21], 0, v[128:129]
	global_load_dwordx4 v[200:203], v[24:25], off
	global_load_dwordx4 v[204:207], v[24:25], off offset:64
	global_load_dwordx4 v[208:211], v[24:25], off offset:512
	global_load_dwordx4 v[212:215], v[24:25], off offset:576
	v_lshl_add_u64 v[18:19], v[18:19], 1, v[132:133]
	s_waitcnt vmcnt(0)
	v_pk_add_f32 v[12:13], v[12:13], v[200:201]
	v_pk_add_f32 v[14:15], v[14:15], v[202:203]
	v_pk_mul_f32 v[26:27], v[12:13], v[12:13]
	global_store_dwordx4 v[24:25], v[12:15], off
	v_pk_mul_f32 v[28:29], v[14:15], v[14:15]
	v_pk_add_f32 v[8:9], v[8:9], v[204:205]
	v_pk_add_f32 v[10:11], v[10:11], v[206:207]
	v_cvt_pk_bf16_f32 v12, v12, v13
	v_cvt_pk_bf16_f32 v13, v14, v15
	v_cvt_pk_bf16_f32 v14, v8, v9
	v_cvt_pk_bf16_f32 v15, v10, v11
	s_nop 0
	v_permlane16_swap_b32_e32 v12, v14
	v_permlane16_swap_b32_e32 v13, v15
	global_store_dwordx4 v[24:25], v[8:11], off offset:64
	global_store_dwordx4 v[18:19], v[12:15], off
	v_pk_mul_f32 v[20:21], v[8:9], v[8:9]
	v_pk_mul_f32 v[22:23], v[10:11], v[10:11]
	v_add_f32_e32 v20, v20, v21
	v_add_f32_e32 v21, v26, v27
	v_add_f32_e32 v20, v22, v20
	v_add_f32_e32 v21, v28, v21
	v_add_f32_e32 v20, v23, v20
	v_add_f32_e32 v21, v29, v21
	v_add_f32_e32 v20, v21, v20
	v_pk_add_f32 v[4:5], v[4:5], v[208:209]
	v_pk_add_f32 v[6:7], v[6:7], v[210:211]
	v_pk_mul_f32 v[12:13], v[4:5], v[4:5]
	v_pk_mul_f32 v[14:15], v[6:7], v[6:7]
	v_add_f32_e32 v12, v12, v13
	v_add_f32_e32 v12, v14, v12
	v_add_f32_e32 v12, v15, v12
	v_add_f32_e32 v12, v20, v12
	global_store_dwordx4 v[24:25], v[4:7], off offset:512
	v_pk_add_f32 v[0:1], v[0:1], v[212:213]
	v_pk_add_f32 v[2:3], v[2:3], v[214:215]
	v_pk_mul_f32 v[8:9], v[0:1], v[0:1]
	v_pk_mul_f32 v[10:11], v[2:3], v[2:3]
	v_add_f32_e32 v8, v8, v9
	v_add_f32_e32 v8, v10, v8
	v_add_f32_e32 v8, v11, v8
	v_add_f32_e32 v8, v12, v8
	global_store_dwordx4 v[24:25], v[0:3], off offset:576
	v_cvt_pk_bf16_f32 v4, v4, v5
	v_cvt_pk_bf16_f32 v5, v6, v7
	v_cvt_pk_bf16_f32 v6, v0, v1
	ds_bpermute_b32 v0, v121, v8
	v_cvt_pk_bf16_f32 v7, v2, v3
	v_permlane16_swap_b32_e32 v4, v6
	s_nop 0
	v_permlane16_swap_b32_e32 v5, v7
	s_waitcnt lgkmcnt(0)
	v_add_f32_e32 v0, v8, v0
	ds_bpermute_b32 v1, v120, v0
	global_store_dwordx4 v[18:19], v[4:7], off offset:256
	s_and_saveexec_b64 s[22:23], vcc
	s_cbranch_execz .LBB0_961
	v_lshlrev_b64 v[2:3], 7, v[16:17]
	v_lshl_add_u64 v[2:3], s[26:27], 0, v[2:3]
	s_waitcnt lgkmcnt(0)
	v_add_f32_e32 v0, v0, v1
	global_store_dword v[2:3], v0, off
	s_branch .LBB0_961

; DEVINL int opaque_tid(int wv) { int t = (wv << 6) | (int)__builtin_amdgcn_mbcnt_hi(~0u, __builtin_amdgcn_mbcnt_lo(~0u, 0u)); asm volatile("" : "+v"(t)); return t; }
; DEVINL float shx(float v, int m, int lane) { return __int_as_float(__builtin_amdgcn_ds_bpermute((lane ^ m) << 2, __float_as_int(v))); }
; DEVINL void phase_gemm_res(const Params& p, const u16* A, int lda, const u16* B, int K, const float* resid, char* smem, int wv) {
;     ...
;   for (int tile = blockIdx.x; tile < NT * MT; tile += gridDim.x) {
;     const int tid = opaque_tid(wv), lane = tid & 63, wid = __builtin_amdgcn_readfirstlane(tid >> 6), wr = wid >> 2, wc = wid & 3, fr = lane & 15, fq = lane >> 4;
;     int pm, pn; tile_map(tile, MT, NT, pm, pn);
;     const int m0 = pm * 256, n0 = pn * 256;
;     f32x4 acc[2][2][4][2];
;     gemm8_mainloop(A, lda, B, K, K, m0, n0, acc, smem, tid);
;     if (tile + (int)gridDim.x < NT * MT) { int pm2, pn2; tile_map(tile + gridDim.x, MT, NT, pm2, pn2); gemm8_issue(A, lda, B, K, pm2 * 256, pn2 * 256, smem, tid); }
; #pragma unroll
;     for (int ai = 0; ai < 2; ++ai)
; #pragma unroll
;       for (int m = 0; m < 4; ++m) {
;         int row = m0 + ai * 128 + wr * 64 + m * 16 + fr;
;         size_t off = (size_t)row * DM + n0 + wc * 32 + fq * 4;
;         size_t offw = (size_t)row * DM + n0 + wc * 32 + (fq & 1) * 16 + (fq >> 1) * 8;
;         float ss = 0.f;
; #pragma unroll
;         for (int bj = 0; bj < 2; ++bj) {
;           f32x4 vv[2];
; #pragma unroll
;           for (int n = 0; n < 2; ++n) {
;             float4 rv = *(const float4*)(resid + off + bj * 128 + n * 16);
;             f32x4 v = acc[ai][bj][m][n];
;             v[0] += rv.x; v[1] += rv.y; v[2] += rv.z; v[3] += rv.w;
;             float4 ov; ov.x = v[0]; ov.y = v[1]; ov.z = v[2]; ov.w = v[3];
;             *(float4*)(out + off + bj * 128 + n * 16) = ov;
;             ss += sumsq4(v);
;             vv[n] = v;
;           }
;           *(u32x4*)(xb + offw + bj * 128) = widen2(vv[0], vv[1]);
;         }
;         ss += shx(ss, 16, lane); ss += shx(ss, 32, lane);
;         if (fq == 0) part[(size_t)row * 32 + pn * 4 + wc] = ss;
;       }
.LBB0_1876:
	s_ashr_i32 s25, s29, 2
	s_andn2_b32 s25, s25, 63
	v_or_b32_e32 v128, s25, v128
	s_bfe_u32 s37, s29, 0x20006
	v_add_u32_e32 v132, s24, v128
	s_lshl_b32 s24, s37, 5
	v_lshrrev_b32_e32 v128, 2, v151
	v_and_b32_e32 v130, 16, v151
	v_ashrrev_i32_e32 v133, 31, v132
	s_or_b32 s22, s22, s24
	v_and_b32_e32 v136, 12, v128
	v_and_or_b32 v128, v128, 8, v130
	v_lshlrev_b64 v[134:135], 11, v[132:133]
	v_lshlrev_b32_e32 v128, 1, v128
	v_lshl_add_u64 v[142:143], v[134:135], 0, s[22:23]
	v_lshl_add_u64 v[130:131], s[90:91], 0, v[128:129]
	v_lshl_add_u64 v[134:135], v[142:143], 2, s[92:93]
	v_lshlrev_b32_e32 v128, 2, v136
	v_lshl_add_u64 v[146:147], v[134:135], 0, v[128:129]
	global_load_dwordx4 v[200:203], v[146:147], off
	global_load_dwordx4 v[204:207], v[146:147], off offset:64
	global_load_dwordx4 v[208:211], v[146:147], off offset:512
	global_load_dwordx4 v[212:215], v[146:147], off offset:576
	v_lshl_add_u64 v[148:149], v[142:143], 1, v[130:131]
	s_lshl_b32 s24, s28, 2
	s_ashr_i32 s25, s24, 31
	s_lshl_b64 s[24:25], s[24:25], 2
	s_add_u32 s24, s60, s24
	s_addc_u32 s25, s61, s25
	s_lshl_b32 s28, s37, 2
	s_add_u32 s24, s24, s28
	s_addc_u32 s25, s25, 0
	s_waitcnt vmcnt(0)
	v_pk_add_f32 v[124:125], v[124:125], v[200:201]
	v_pk_add_f32 v[126:127], v[126:127], v[202:203]
	v_pk_add_f32 v[134:135], v[120:121], v[204:205]
	v_pk_add_f32 v[136:137], v[122:123], v[206:207]
	v_cvt_pk_bf16_f32 v120, v124, v125
	v_cvt_pk_bf16_f32 v121, v126, v127
	v_cvt_pk_bf16_f32 v122, v134, v135
	v_cvt_pk_bf16_f32 v123, v136, v137
	s_nop 0
	v_permlane16_swap_b32_e32 v120, v122
	v_permlane16_swap_b32_e32 v121, v123
	global_store_dwordx4 v[146:147], v[124:127], off
	global_store_dwordx4 v[146:147], v[134:137], off offset:64
	global_store_dwordx4 v[148:149], v[120:123], off
	s_nop 1
	v_and_b32_e32 v120, 63, v151
	v_lshlrev_b32_e32 v122, 2, v120
	v_cmp_gt_u32_e32 vcc, 16, v120
	v_xor_b32_e32 v121, 64, v122
	v_xor_b32_e32 v120, 0x80, v122
	v_pk_mul_f32 v[122:123], v[124:125], v[124:125]
	v_pk_mul_f32 v[124:125], v[126:127], v[126:127]
	v_pk_mul_f32 v[126:127], v[134:135], v[134:135]
	v_pk_mul_f32 v[134:135], v[136:137], v[136:137]
	v_add_f32_e32 v126, v126, v127
	v_add_f32_e32 v122, v122, v123
	v_add_f32_e32 v123, v134, v126
	v_add_f32_e32 v122, v124, v122
	v_add_f32_e32 v123, v135, v123
	v_add_f32_e32 v122, v125, v122
	v_add_f32_e32 v136, v122, v123
	v_pk_add_f32 v[112:113], v[112:113], v[208:209]
	v_pk_add_f32 v[114:115], v[114:115], v[210:211]
	v_pk_add_f32 v[116:117], v[116:117], v[212:213]
	v_pk_mul_f32 v[122:123], v[112:113], v[112:113]
	v_pk_add_f32 v[118:119], v[118:119], v[214:215]
	v_pk_mul_f32 v[124:125], v[114:115], v[114:115]
	v_pk_mul_f32 v[126:127], v[116:117], v[116:117]
	v_add_f32_e32 v122, v122, v123
	v_pk_mul_f32 v[134:135], v[118:119], v[118:119]
	v_add_f32_e32 v123, v126, v127
	v_add_f32_e32 v122, v124, v122
	v_add_f32_e32 v123, v134, v123
	v_add_f32_e32 v122, v125, v122
	v_add_f32_e32 v123, v135, v123
	v_add_f32_e32 v122, v136, v122
	v_add_f32_e32 v126, v122, v123
	ds_bpermute_b32 v127, v121, v126
	global_store_dwordx4 v[146:147], v[112:115], off offset:512
	v_cvt_pk_bf16_f32 v122, v112, v113
	v_cvt_pk_bf16_f32 v123, v114, v115
	v_cvt_pk_bf16_f32 v124, v116, v117
	s_waitcnt lgkmcnt(0)
	v_add_f32_e32 v112, v126, v127
	ds_bpermute_b32 v113, v120, v112
	v_cvt_pk_bf16_f32 v125, v118, v119
	v_permlane16_swap_b32_e32 v122, v124
	s_nop 0
	v_permlane16_swap_b32_e32 v123, v125
	global_store_dwordx4 v[146:147], v[116:119], off offset:576
	global_store_dwordx4 v[148:149], v[122:125], off offset:256
	s_and_saveexec_b64 s[28:29], vcc
	s_cbranch_execz .LBB0_1878
	v_lshlrev_b64 v[114:115], 7, v[132:133]
	v_lshl_add_u64 v[114:115], s[24:25], 0, v[114:115]
	s_waitcnt lgkmcnt(0)
	v_add_f32_e32 v112, v112, v113
	global_store_dword v[114:115], v112, off
.LBB0_1878:
	s_or_b64 exec, exec, s[28:29]
	v_or_b32_e32 v112, 16, v132
	s_waitcnt lgkmcnt(0)
	v_ashrrev_i32_e32 v113, 31, v112
	v_lshlrev_b64 v[114:115], 11, v[112:113]
	v_lshl_add_u64 v[118:119], v[114:115], 0, s[22:23]
	v_lshl_add_u64 v[114:115], v[118:119], 2, s[92:93]
	v_lshl_add_u64 v[126:127], v[114:115], 0, v[128:129]
	global_load_dwordx4 v[200:203], v[126:127], off
	global_load_dwordx4 v[204:207], v[126:127], off offset:64
	global_load_dwordx4 v[208:211], v[126:127], off offset:512
	global_load_dwordx4 v[212:215], v[126:127], off offset:576
	v_lshl_add_u64 v[118:119], v[118:119], 1, v[130:131]
	s_waitcnt vmcnt(0)
	v_pk_add_f32 v[108:109], v[108:109], v[200:201]
	v_pk_add_f32 v[110:111], v[110:111], v[202:203]
	v_pk_add_f32 v[104:105], v[104:105], v[204:205]
	v_pk_add_f32 v[106:107], v[106:107], v[206:207]
	v_cvt_pk_bf16_f32 v114, v108, v109
	v_cvt_pk_bf16_f32 v115, v110, v111
	v_cvt_pk_bf16_f32 v116, v104, v105
	v_cvt_pk_bf16_f32 v117, v106, v107
	s_nop 0
	v_permlane16_swap_b32_e32 v114, v116
	v_permlane16_swap_b32_e32 v115, v117
	global_store_dwordx4 v[126:127], v[108:111], off
	global_store_dwordx4 v[126:127], v[104:107], off offset:64
	global_store_dwordx4 v[118:119], v[114:117], off
	s_nop 0
	v_pk_mul_f32 v[108:109], v[108:109], v[108:109]
	v_pk_mul_f32 v[104:105], v[104:105], v[104:105]
	v_pk_mul_f32 v[110:111], v[110:111], v[110:111]
	v_pk_mul_f32 v[106:107], v[106:107], v[106:107]
	v_add_f32_e32 v104, v104, v105
	v_add_f32_e32 v105, v108, v109
	v_add_f32_e32 v104, v106, v104
	v_add_f32_e32 v105, v110, v105
	v_add_f32_e32 v104, v107, v104
	v_add_f32_e32 v105, v111, v105
	v_add_f32_e32 v133, v105, v104
	v_pk_add_f32 v[96:97], v[96:97], v[208:209]
	v_pk_add_f32 v[98:99], v[98:99], v[210:211]
	v_pk_add_f32 v[100:101], v[100:101], v[212:213]
	v_pk_mul_f32 v[104:105], v[96:97], v[96:97]
	v_pk_add_f32 v[102:103], v[102:103], v[214:215]
	v_pk_mul_f32 v[106:107], v[98:99], v[98:99]
	v_pk_mul_f32 v[108:109], v[100:101], v[100:101]
	v_add_f32_e32 v104, v104, v105
	v_pk_mul_f32 v[110:111], v[102:103], v[102:103]
	v_add_f32_e32 v105, v108, v109
	v_add_f32_e32 v104, v106, v104
	v_add_f32_e32 v105, v110, v105
	v_add_f32_e32 v104, v107, v104
	v_add_f32_e32 v105, v111, v105
	v_add_f32_e32 v104, v133, v104
	v_add_f32_e32 v108, v104, v105
	ds_bpermute_b32 v109, v121, v108
	global_store_dwordx4 v[126:127], v[96:99], off offset:512
	v_cvt_pk_bf16_f32 v104, v96, v97
	v_cvt_pk_bf16_f32 v105, v98, v99
	v_cvt_pk_bf16_f32 v106, v100, v101
	s_waitcnt lgkmcnt(0)
	v_add_f32_e32 v96, v108, v109
	ds_bpermute_b32 v97, v120, v96
	v_cvt_pk_bf16_f32 v107, v102, v103
	v_permlane16_swap_b32_e32 v104, v106
	s_nop 0
	v_permlane16_swap_b32_e32 v105, v107
	global_store_dwordx4 v[126:127], v[100:103], off offset:576
	global_store_dwordx4 v[118:119], v[104:107], off offset:256
	s_and_saveexec_b64 s[28:29], vcc
	s_cbranch_execz .LBB0_1880
	v_lshlrev_b64 v[98:99], 7, v[112:113]
	v_lshl_add_u64 v[98:99], s[24:25], 0, v[98:99]
	s_waitcnt lgkmcnt(0)
	v_add_f32_e32 v96, v96, v97
	global_store_dword v[98:99], v96, off
; DEVINL float shx(float v, int m, int lane) { return __int_as_float(__builtin_amdgcn_ds_bpermute((lane ^ m) << 2, __float_as_int(v))); }
; DEVINL void phase_gemm_res(const Params& p, const u16* A, int lda, const u16* B, int K, const float* resid, char* smem, int wv) {
;     ...
; #pragma unroll
;     for (int ai = 0; ai < 2; ++ai)
; #pragma unroll
;       for (int m = 0; m < 4; ++m) {
;         int row = m0 + ai * 128 + wr * 64 + m * 16 + fr;
;         size_t off = (size_t)row * DM + n0 + wc * 32 + fq * 4;
;         size_t offw = (size_t)row * DM + n0 + wc * 32 + (fq & 1) * 16 + (fq >> 1) * 8;
;         float ss = 0.f;
; #pragma unroll
;         for (int bj = 0; bj < 2; ++bj) {
;           f32x4 vv[2];
; #pragma unroll
;           for (int n = 0; n < 2; ++n) {
;             float4 rv = *(const float4*)(resid + off + bj * 128 + n * 16);
;             f32x4 v = acc[ai][bj][m][n];
;             v[0] += rv.x; v[1] += rv.y; v[2] += rv.z; v[3] += rv.w;
;             float4 ov; ov.x = v[0]; ov.y = v[1]; ov.z = v[2]; ov.w = v[3];
;             *(float4*)(out + off + bj * 128 + n * 16) = ov;
;             ss += sumsq4(v);
;             vv[n] = v;
;           }
;           *(u32x4*)(xb + offw + bj * 128) = widen2(vv[0], vv[1]);
;         }
;         ss += shx(ss, 16, lane); ss += shx(ss, 32, lane);
;         if (fq == 0) part[(size_t)row * 32 + pn * 4 + wc] = ss;
;       }
.LBB0_1880:
	s_or_b64 exec, exec, s[28:29]
	v_or_b32_e32 v96, 32, v132
	s_waitcnt lgkmcnt(0)
	v_ashrrev_i32_e32 v97, 31, v96
	v_lshlrev_b64 v[98:99], 11, v[96:97]
	v_lshl_add_u64 v[106:107], v[98:99], 0, s[22:23]
	v_lshl_add_u64 v[98:99], v[106:107], 2, s[92:93]
	v_lshl_add_u64 v[108:109], v[98:99], 0, v[128:129]
	global_load_dwordx4 v[200:203], v[108:109], off
	global_load_dwordx4 v[204:207], v[108:109], off offset:64
	global_load_dwordx4 v[208:211], v[108:109], off offset:512
	global_load_dwordx4 v[212:215], v[108:109], off offset:576
	v_lshl_add_u64 v[106:107], v[106:107], 1, v[130:131]
	s_waitcnt vmcnt(0)
	v_pk_add_f32 v[92:93], v[92:93], v[200:201]
	v_pk_add_f32 v[94:95], v[94:95], v[202:203]
	v_pk_add_f32 v[88:89], v[88:89], v[204:205]
	v_pk_add_f32 v[90:91], v[90:91], v[206:207]
	v_cvt_pk_bf16_f32 v98, v92, v93
	v_cvt_pk_bf16_f32 v99, v94, v95
	v_cvt_pk_bf16_f32 v100, v88, v89
	v_cvt_pk_bf16_f32 v101, v90, v91
	s_nop 0
	v_permlane16_swap_b32_e32 v98, v100
	v_permlane16_swap_b32_e32 v99, v101
	global_store_dwordx4 v[108:109], v[92:95], off
	global_store_dwordx4 v[108:109], v[88:91], off offset:64
	global_store_dwordx4 v[106:107], v[98:101], off
	s_nop 0
	v_pk_mul_f32 v[92:93], v[92:93], v[92:93]
	v_pk_mul_f32 v[88:89], v[88:89], v[88:89]
	v_pk_mul_f32 v[94:95], v[94:95], v[94:95]
	v_pk_mul_f32 v[90:91], v[90:91], v[90:91]
	v_add_f32_e32 v88, v88, v89
	v_add_f32_e32 v89, v92, v93
	v_add_f32_e32 v88, v90, v88
	v_add_f32_e32 v89, v94, v89
	v_add_f32_e32 v88, v91, v88
	v_add_f32_e32 v89, v95, v89
	v_add_f32_e32 v110, v89, v88
	v_pk_add_f32 v[80:81], v[80:81], v[208:209]
	v_pk_add_f32 v[82:83], v[82:83], v[210:211]
	v_pk_add_f32 v[84:85], v[84:85], v[212:213]
	v_pk_mul_f32 v[88:89], v[80:81], v[80:81]
	v_pk_add_f32 v[86:87], v[86:87], v[214:215]
	v_pk_mul_f32 v[90:91], v[82:83], v[82:83]
	v_pk_mul_f32 v[92:93], v[84:85], v[84:85]
	v_add_f32_e32 v88, v88, v89
	v_pk_mul_f32 v[94:95], v[86:87], v[86:87]
	v_add_f32_e32 v89, v92, v93
	v_add_f32_e32 v88, v90, v88
	v_add_f32_e32 v89, v94, v89
	v_add_f32_e32 v88, v91, v88
	v_add_f32_e32 v89, v95, v89
	v_add_f32_e32 v88, v110, v88
	v_add_f32_e32 v92, v88, v89
	ds_bpermute_b32 v93, v121, v92
	global_store_dwordx4 v[108:109], v[80:83], off offset:512
	v_cvt_pk_bf16_f32 v88, v80, v81
	v_cvt_pk_bf16_f32 v89, v82, v83
	v_cvt_pk_bf16_f32 v90, v84, v85
	s_waitcnt lgkmcnt(0)
	v_add_f32_e32 v80, v92, v93
	ds_bpermute_b32 v81, v120, v80
	v_cvt_pk_bf16_f32 v91, v86, v87
	v_permlane16_swap_b32_e32 v88, v90
	s_nop 0
	v_permlane16_swap_b32_e32 v89, v91
	global_store_dwordx4 v[108:109], v[84:87], off offset:576
	global_store_dwordx4 v[106:107], v[88:91], off offset:256
	s_and_saveexec_b64 s[28:29], vcc
	s_cbranch_execz .LBB0_1882
	v_lshlrev_b64 v[82:83], 7, v[96:97]
	v_lshl_add_u64 v[82:83], s[24:25], 0, v[82:83]
	s_waitcnt lgkmcnt(0)
	v_add_f32_e32 v80, v80, v81
	global_store_dword v[82:83], v80, off
.LBB0_1882:
	s_or_b64 exec, exec, s[28:29]
	v_or_b32_e32 v80, 48, v132
	s_waitcnt lgkmcnt(0)
	v_ashrrev_i32_e32 v81, 31, v80
	v_lshlrev_b64 v[82:83], 11, v[80:81]
	v_lshl_add_u64 v[90:91], v[82:83], 0, s[22:23]
	v_lshl_add_u64 v[82:83], v[90:91], 2, s[92:93]
	v_lshl_add_u64 v[92:93], v[82:83], 0, v[128:129]
	global_load_dwordx4 v[200:203], v[92:93], off
	global_load_dwordx4 v[204:207], v[92:93], off offset:64
	global_load_dwordx4 v[208:211], v[92:93], off offset:512
	global_load_dwordx4 v[212:215], v[92:93], off offset:576
	v_lshl_add_u64 v[90:91], v[90:91], 1, v[130:131]
	s_waitcnt vmcnt(0)
	v_pk_add_f32 v[76:77], v[76:77], v[200:201]
	v_pk_add_f32 v[78:79], v[78:79], v[202:203]
	v_pk_add_f32 v[72:73], v[72:73], v[204:205]
	v_pk_add_f32 v[74:75], v[74:75], v[206:207]
	v_cvt_pk_bf16_f32 v82, v76, v77
	v_cvt_pk_bf16_f32 v83, v78, v79
	v_cvt_pk_bf16_f32 v84, v72, v73
	v_cvt_pk_bf16_f32 v85, v74, v75
	s_nop 0
	v_permlane16_swap_b32_e32 v82, v84
	v_permlane16_swap_b32_e32 v83, v85
	global_store_dwordx4 v[92:93], v[76:79], off
	global_store_dwordx4 v[92:93], v[72:75], off offset:64
	global_store_dwordx4 v[90:91], v[82:85], off
	s_nop 0
	v_pk_mul_f32 v[76:77], v[76:77], v[76:77]
	v_pk_mul_f32 v[72:73], v[72:73], v[72:73]
	v_pk_mul_f32 v[78:79], v[78:79], v[78:79]
	v_pk_mul_f32 v[74:75], v[74:75], v[74:75]
	v_add_f32_e32 v72, v72, v73
	v_add_f32_e32 v73, v76, v77
	v_add_f32_e32 v72, v74, v72
	v_add_f32_e32 v73, v78, v73
	v_add_f32_e32 v72, v75, v72
	v_add_f32_e32 v73, v79, v73
	v_add_f32_e32 v94, v73, v72
	v_pk_add_f32 v[64:65], v[64:65], v[208:209]
	v_pk_add_f32 v[66:67], v[66:67], v[210:211]
	v_pk_add_f32 v[68:69], v[68:69], v[212:213]
	v_pk_mul_f32 v[72:73], v[64:65], v[64:65]
	v_pk_add_f32 v[70:71], v[70:71], v[214:215]
	v_pk_mul_f32 v[74:75], v[66:67], v[66:67]
	v_pk_mul_f32 v[76:77], v[68:69], v[68:69]
	v_add_f32_e32 v72, v72, v73
	v_pk_mul_f32 v[78:79], v[70:71], v[70:71]
	v_add_f32_e32 v73, v76, v77
	v_add_f32_e32 v72, v74, v72
	v_add_f32_e32 v73, v78, v73
	v_add_f32_e32 v72, v75, v72
	v_add_f32_e32 v73, v79, v73
	v_add_f32_e32 v72, v94, v72
	v_add_f32_e32 v76, v72, v73
	ds_bpermute_b32 v77, v121, v76
	global_store_dwordx4 v[92:93], v[64:67], off offset:512
	v_cvt_pk_bf16_f32 v72, v64, v65
	v_cvt_pk_bf16_f32 v73, v66, v67
	v_cvt_pk_bf16_f32 v74, v68, v69
	s_waitcnt lgkmcnt(0)
	v_add_f32_e32 v64, v76, v77
	ds_bpermute_b32 v65, v120, v64
	v_cvt_pk_bf16_f32 v75, v70, v71
	v_permlane16_swap_b32_e32 v72, v74
	s_nop 0
	v_permlane16_swap_b32_e32 v73, v75
	global_store_dwordx4 v[92:93], v[68:71], off offset:576
	global_store_dwordx4 v[90:91], v[72:75], off offset:256
	s_and_saveexec_b64 s[28:29], vcc
	s_cbranch_execz .LBB0_1884
	v_lshlrev_b64 v[66:67], 7, v[80:81]
	v_lshl_add_u64 v[66:67], s[24:25], 0, v[66:67]
	s_waitcnt lgkmcnt(0)
	v_add_f32_e32 v64, v64, v65
	global_store_dword v[66:67], v64, off
; DEVINL float shx(float v, int m, int lane) { return __int_as_float(__builtin_amdgcn_ds_bpermute((lane ^ m) << 2, __float_as_int(v))); }
; DEVINL void phase_gemm_res(const Params& p, const u16* A, int lda, const u16* B, int K, const float* resid, char* smem, int wv) {
;     ...
; #pragma unroll
;     for (int ai = 0; ai < 2; ++ai)
; #pragma unroll
;       for (int m = 0; m < 4; ++m) {
;         int row = m0 + ai * 128 + wr * 64 + m * 16 + fr;
;         size_t off = (size_t)row * DM + n0 + wc * 32 + fq * 4;
;         size_t offw = (size_t)row * DM + n0 + wc * 32 + (fq & 1) * 16 + (fq >> 1) * 8;
;         float ss = 0.f;
; #pragma unroll
;         for (int bj = 0; bj < 2; ++bj) {
;           f32x4 vv[2];
; #pragma unroll
;           for (int n = 0; n < 2; ++n) {
;             float4 rv = *(const float4*)(resid + off + bj * 128 + n * 16);
;             f32x4 v = acc[ai][bj][m][n];
;             v[0] += rv.x; v[1] += rv.y; v[2] += rv.z; v[3] += rv.w;
;             float4 ov; ov.x = v[0]; ov.y = v[1]; ov.z = v[2]; ov.w = v[3];
;             *(float4*)(out + off + bj * 128 + n * 16) = ov;
;             ss += sumsq4(v);
;             vv[n] = v;
;           }
;           *(u32x4*)(xb + offw + bj * 128) = widen2(vv[0], vv[1]);
;         }
;         ss += shx(ss, 16, lane); ss += shx(ss, 32, lane);
;         if (fq == 0) part[(size_t)row * 32 + pn * 4 + wc] = ss;
;       }
.LBB0_1884:
	s_or_b64 exec, exec, s[28:29]
	v_add_u32_e32 v64, 0x80, v132
	s_waitcnt lgkmcnt(0)
	v_ashrrev_i32_e32 v65, 31, v64
	v_lshlrev_b64 v[66:67], 11, v[64:65]
	v_lshl_add_u64 v[74:75], v[66:67], 0, s[22:23]
	v_lshl_add_u64 v[66:67], v[74:75], 2, s[92:93]
	v_lshl_add_u64 v[76:77], v[66:67], 0, v[128:129]
	global_load_dwordx4 v[200:203], v[76:77], off
	global_load_dwordx4 v[204:207], v[76:77], off offset:64
	global_load_dwordx4 v[208:211], v[76:77], off offset:512
	global_load_dwordx4 v[212:215], v[76:77], off offset:576
	v_lshl_add_u64 v[74:75], v[74:75], 1, v[130:131]
	s_waitcnt vmcnt(0)
	v_pk_add_f32 v[60:61], v[60:61], v[200:201]
	v_pk_add_f32 v[62:63], v[62:63], v[202:203]
	v_pk_add_f32 v[56:57], v[56:57], v[204:205]
	v_pk_add_f32 v[58:59], v[58:59], v[206:207]
	v_cvt_pk_bf16_f32 v66, v60, v61
	v_cvt_pk_bf16_f32 v67, v62, v63
	v_cvt_pk_bf16_f32 v68, v56, v57
	v_cvt_pk_bf16_f32 v69, v58, v59
	s_nop 0
	v_permlane16_swap_b32_e32 v66, v68
	v_permlane16_swap_b32_e32 v67, v69
	global_store_dwordx4 v[76:77], v[60:63], off
	global_store_dwordx4 v[76:77], v[56:59], off offset:64
	global_store_dwordx4 v[74:75], v[66:69], off
	s_nop 0
	v_pk_mul_f32 v[60:61], v[60:61], v[60:61]
	v_pk_mul_f32 v[56:57], v[56:57], v[56:57]
	v_pk_mul_f32 v[62:63], v[62:63], v[62:63]
	v_pk_mul_f32 v[58:59], v[58:59], v[58:59]
	v_add_f32_e32 v56, v56, v57
	v_add_f32_e32 v57, v60, v61
	v_add_f32_e32 v56, v58, v56
	v_add_f32_e32 v57, v62, v57
	v_add_f32_e32 v56, v59, v56
	v_add_f32_e32 v57, v63, v57
	v_add_f32_e32 v78, v57, v56
	v_pk_add_f32 v[48:49], v[48:49], v[208:209]
	v_pk_add_f32 v[50:51], v[50:51], v[210:211]
	v_pk_add_f32 v[52:53], v[52:53], v[212:213]
	v_pk_mul_f32 v[56:57], v[48:49], v[48:49]
	v_pk_add_f32 v[54:55], v[54:55], v[214:215]
	v_pk_mul_f32 v[58:59], v[50:51], v[50:51]
	v_pk_mul_f32 v[60:61], v[52:53], v[52:53]
	v_add_f32_e32 v56, v56, v57
	v_pk_mul_f32 v[62:63], v[54:55], v[54:55]
	v_add_f32_e32 v57, v60, v61
	v_add_f32_e32 v56, v58, v56
	v_add_f32_e32 v57, v62, v57
	v_add_f32_e32 v56, v59, v56
	v_add_f32_e32 v57, v63, v57
	v_add_f32_e32 v56, v78, v56
	v_add_f32_e32 v60, v56, v57
	ds_bpermute_b32 v61, v121, v60
	global_store_dwordx4 v[76:77], v[48:51], off offset:512
	v_cvt_pk_bf16_f32 v56, v48, v49
	v_cvt_pk_bf16_f32 v57, v50, v51
	v_cvt_pk_bf16_f32 v58, v52, v53
	s_waitcnt lgkmcnt(0)
	v_add_f32_e32 v48, v60, v61
	ds_bpermute_b32 v49, v120, v48
	v_cvt_pk_bf16_f32 v59, v54, v55
	v_permlane16_swap_b32_e32 v56, v58
	s_nop 0
	v_permlane16_swap_b32_e32 v57, v59
	global_store_dwordx4 v[76:77], v[52:55], off offset:576
	global_store_dwordx4 v[74:75], v[56:59], off offset:256
	s_and_saveexec_b64 s[28:29], vcc
	s_cbranch_execz .LBB0_1886
	v_lshlrev_b64 v[50:51], 7, v[64:65]
	v_lshl_add_u64 v[50:51], s[24:25], 0, v[50:51]
	s_waitcnt lgkmcnt(0)
	v_add_f32_e32 v48, v48, v49
	global_store_dword v[50:51], v48, off
.LBB0_1886:
	s_or_b64 exec, exec, s[28:29]
	v_add_u32_e32 v48, 0x90, v132
	s_waitcnt lgkmcnt(0)
	v_ashrrev_i32_e32 v49, 31, v48
	v_lshlrev_b64 v[50:51], 11, v[48:49]
	v_lshl_add_u64 v[58:59], v[50:51], 0, s[22:23]
	v_lshl_add_u64 v[50:51], v[58:59], 2, s[92:93]
	v_lshl_add_u64 v[60:61], v[50:51], 0, v[128:129]
	global_load_dwordx4 v[200:203], v[60:61], off
	global_load_dwordx4 v[204:207], v[60:61], off offset:64
	global_load_dwordx4 v[208:211], v[60:61], off offset:512
	global_load_dwordx4 v[212:215], v[60:61], off offset:576
	v_lshl_add_u64 v[58:59], v[58:59], 1, v[130:131]
	s_waitcnt vmcnt(0)
	v_pk_add_f32 v[44:45], v[44:45], v[200:201]
	v_pk_add_f32 v[46:47], v[46:47], v[202:203]
	v_pk_add_f32 v[40:41], v[40:41], v[204:205]
	v_pk_add_f32 v[42:43], v[42:43], v[206:207]
	v_cvt_pk_bf16_f32 v50, v44, v45
	v_cvt_pk_bf16_f32 v51, v46, v47
	v_cvt_pk_bf16_f32 v52, v40, v41
	v_cvt_pk_bf16_f32 v53, v42, v43
	s_nop 0
	v_permlane16_swap_b32_e32 v50, v52
	v_permlane16_swap_b32_e32 v51, v53
	global_store_dwordx4 v[60:61], v[44:47], off
	global_store_dwordx4 v[60:61], v[40:43], off offset:64
	global_store_dwordx4 v[58:59], v[50:53], off
	s_nop 0
	v_pk_mul_f32 v[44:45], v[44:45], v[44:45]
	v_pk_mul_f32 v[40:41], v[40:41], v[40:41]
	v_pk_mul_f32 v[46:47], v[46:47], v[46:47]
	v_pk_mul_f32 v[42:43], v[42:43], v[42:43]
	v_add_f32_e32 v40, v40, v41
	v_add_f32_e32 v41, v44, v45
	v_add_f32_e32 v40, v42, v40
	v_add_f32_e32 v41, v46, v41
	v_add_f32_e32 v40, v43, v40
	v_add_f32_e32 v41, v47, v41
	v_add_f32_e32 v62, v41, v40
	v_pk_add_f32 v[32:33], v[32:33], v[208:209]
	v_pk_add_f32 v[34:35], v[34:35], v[210:211]
	v_pk_add_f32 v[36:37], v[36:37], v[212:213]
	v_pk_mul_f32 v[40:41], v[32:33], v[32:33]
	v_pk_add_f32 v[38:39], v[38:39], v[214:215]
	v_pk_mul_f32 v[42:43], v[34:35], v[34:35]
	v_pk_mul_f32 v[44:45], v[36:37], v[36:37]
	v_add_f32_e32 v40, v40, v41
	v_pk_mul_f32 v[46:47], v[38:39], v[38:39]
	v_add_f32_e32 v41, v44, v45
	v_add_f32_e32 v40, v42, v40
	v_add_f32_e32 v41, v46, v41
	v_add_f32_e32 v40, v43, v40
	v_add_f32_e32 v41, v47, v41
	v_add_f32_e32 v40, v62, v40
	v_add_f32_e32 v44, v40, v41
	ds_bpermute_b32 v45, v121, v44
	global_store_dwordx4 v[60:61], v[32:35], off offset:512
	v_cvt_pk_bf16_f32 v40, v32, v33
	v_cvt_pk_bf16_f32 v41, v34, v35
	v_cvt_pk_bf16_f32 v42, v36, v37
	s_waitcnt lgkmcnt(0)
	v_add_f32_e32 v32, v44, v45
	ds_bpermute_b32 v33, v120, v32
	v_cvt_pk_bf16_f32 v43, v38, v39
	v_permlane16_swap_b32_e32 v40, v42
	s_nop 0
	v_permlane16_swap_b32_e32 v41, v43
	global_store_dwordx4 v[60:61], v[36:39], off offset:576
	global_store_dwordx4 v[58:59], v[40:43], off offset:256
	s_and_saveexec_b64 s[28:29], vcc
	s_cbranch_execz .LBB0_1888
	v_lshlrev_b64 v[34:35], 7, v[48:49]
	v_lshl_add_u64 v[34:35], s[24:25], 0, v[34:35]
	s_waitcnt lgkmcnt(0)
	v_add_f32_e32 v32, v32, v33
	global_store_dword v[34:35], v32, off
; DEVINL float shx(float v, int m, int lane) { return __int_as_float(__builtin_amdgcn_ds_bpermute((lane ^ m) << 2, __float_as_int(v))); }
; DEVINL void phase_gemm_res(const Params& p, const u16* A, int lda, const u16* B, int K, const float* resid, char* smem, int wv) {
;     ...
; #pragma unroll
;     for (int ai = 0; ai < 2; ++ai)
; #pragma unroll
;       for (int m = 0; m < 4; ++m) {
;         int row = m0 + ai * 128 + wr * 64 + m * 16 + fr;
;         size_t off = (size_t)row * DM + n0 + wc * 32 + fq * 4;
;         size_t offw = (size_t)row * DM + n0 + wc * 32 + (fq & 1) * 16 + (fq >> 1) * 8;
;         float ss = 0.f;
; #pragma unroll
;         for (int bj = 0; bj < 2; ++bj) {
;           f32x4 vv[2];
; #pragma unroll
;           for (int n = 0; n < 2; ++n) {
;             float4 rv = *(const float4*)(resid + off + bj * 128 + n * 16);
;             f32x4 v = acc[ai][bj][m][n];
;             v[0] += rv.x; v[1] += rv.y; v[2] += rv.z; v[3] += rv.w;
;             float4 ov; ov.x = v[0]; ov.y = v[1]; ov.z = v[2]; ov.w = v[3];
;             *(float4*)(out + off + bj * 128 + n * 16) = ov;
;             ss += sumsq4(v);
;             vv[n] = v;
;           }
;           *(u32x4*)(xb + offw + bj * 128) = widen2(vv[0], vv[1]);
;         }
;         ss += shx(ss, 16, lane); ss += shx(ss, 32, lane);
;         if (fq == 0) part[(size_t)row * 32 + pn * 4 + wc] = ss;
;       }
.LBB0_1888:
	s_or_b64 exec, exec, s[28:29]
	v_add_u32_e32 v32, 0xa0, v132
	s_waitcnt lgkmcnt(0)
	v_ashrrev_i32_e32 v33, 31, v32
	v_lshlrev_b64 v[34:35], 11, v[32:33]
	v_lshl_add_u64 v[42:43], v[34:35], 0, s[22:23]
	v_lshl_add_u64 v[34:35], v[42:43], 2, s[92:93]
	v_lshl_add_u64 v[44:45], v[34:35], 0, v[128:129]
	global_load_dwordx4 v[200:203], v[44:45], off
	global_load_dwordx4 v[204:207], v[44:45], off offset:64
	global_load_dwordx4 v[208:211], v[44:45], off offset:512
	global_load_dwordx4 v[212:215], v[44:45], off offset:576
	v_lshl_add_u64 v[42:43], v[42:43], 1, v[130:131]
	s_waitcnt vmcnt(0)
	v_pk_add_f32 v[28:29], v[28:29], v[200:201]
	v_pk_add_f32 v[30:31], v[30:31], v[202:203]
	v_pk_add_f32 v[24:25], v[24:25], v[204:205]
	v_pk_add_f32 v[26:27], v[26:27], v[206:207]
	v_cvt_pk_bf16_f32 v34, v28, v29
	v_cvt_pk_bf16_f32 v35, v30, v31
	v_cvt_pk_bf16_f32 v36, v24, v25
	v_cvt_pk_bf16_f32 v37, v26, v27
	s_nop 0
	v_permlane16_swap_b32_e32 v34, v36
	v_permlane16_swap_b32_e32 v35, v37
	global_store_dwordx4 v[44:45], v[28:31], off
	global_store_dwordx4 v[44:45], v[24:27], off offset:64
	global_store_dwordx4 v[42:43], v[34:37], off
	s_nop 0
	v_pk_mul_f32 v[28:29], v[28:29], v[28:29]
	v_pk_mul_f32 v[24:25], v[24:25], v[24:25]
	v_pk_mul_f32 v[30:31], v[30:31], v[30:31]
	v_pk_mul_f32 v[26:27], v[26:27], v[26:27]
	v_add_f32_e32 v24, v24, v25
	v_add_f32_e32 v25, v28, v29
	v_add_f32_e32 v24, v26, v24
	v_add_f32_e32 v25, v30, v25
	v_add_f32_e32 v24, v27, v24
	v_add_f32_e32 v25, v31, v25
	v_add_f32_e32 v46, v25, v24
	v_pk_add_f32 v[16:17], v[16:17], v[208:209]
	v_pk_add_f32 v[18:19], v[18:19], v[210:211]
	v_pk_add_f32 v[20:21], v[20:21], v[212:213]
	v_pk_mul_f32 v[24:25], v[16:17], v[16:17]
	v_pk_add_f32 v[22:23], v[22:23], v[214:215]
	v_pk_mul_f32 v[26:27], v[18:19], v[18:19]
	v_pk_mul_f32 v[28:29], v[20:21], v[20:21]
	v_add_f32_e32 v24, v24, v25
	v_pk_mul_f32 v[30:31], v[22:23], v[22:23]
	v_add_f32_e32 v25, v28, v29
	v_add_f32_e32 v24, v26, v24
	v_add_f32_e32 v25, v30, v25
	v_add_f32_e32 v24, v27, v24
	v_add_f32_e32 v25, v31, v25
	v_add_f32_e32 v24, v46, v24
	v_add_f32_e32 v28, v24, v25
	ds_bpermute_b32 v29, v121, v28
	global_store_dwordx4 v[44:45], v[16:19], off offset:512
	v_cvt_pk_bf16_f32 v24, v16, v17
	v_cvt_pk_bf16_f32 v25, v18, v19
	v_cvt_pk_bf16_f32 v26, v20, v21
	s_waitcnt lgkmcnt(0)
	v_add_f32_e32 v16, v28, v29
	ds_bpermute_b32 v17, v120, v16
	v_cvt_pk_bf16_f32 v27, v22, v23
	v_permlane16_swap_b32_e32 v24, v26
	s_nop 0
	v_permlane16_swap_b32_e32 v25, v27
	global_store_dwordx4 v[44:45], v[20:23], off offset:576
	global_store_dwordx4 v[42:43], v[24:27], off offset:256
	s_and_saveexec_b64 s[28:29], vcc
	s_cbranch_execz .LBB0_1890
	v_lshlrev_b64 v[18:19], 7, v[32:33]
	v_lshl_add_u64 v[18:19], s[24:25], 0, v[18:19]
	s_waitcnt lgkmcnt(0)
	v_add_f32_e32 v16, v16, v17
	global_store_dword v[18:19], v16, off
.LBB0_1890:
	s_or_b64 exec, exec, s[28:29]
	v_add_u32_e32 v16, 0xb0, v132
	s_waitcnt lgkmcnt(0)
	v_ashrrev_i32_e32 v17, 31, v16
	v_lshlrev_b64 v[18:19], 11, v[16:17]
	v_lshl_add_u64 v[26:27], v[18:19], 0, s[22:23]
	v_lshl_add_u64 v[18:19], v[26:27], 2, s[92:93]
	v_lshl_add_u64 v[28:29], v[18:19], 0, v[128:129]
	global_load_dwordx4 v[200:203], v[28:29], off
	global_load_dwordx4 v[204:207], v[28:29], off offset:64
	global_load_dwordx4 v[208:211], v[28:29], off offset:512
	global_load_dwordx4 v[212:215], v[28:29], off offset:576
	v_lshl_add_u64 v[26:27], v[26:27], 1, v[130:131]
	s_waitcnt vmcnt(0)
	v_pk_add_f32 v[12:13], v[12:13], v[200:201]
	v_pk_add_f32 v[14:15], v[14:15], v[202:203]
	v_pk_add_f32 v[8:9], v[8:9], v[204:205]
	v_pk_add_f32 v[10:11], v[10:11], v[206:207]
	v_cvt_pk_bf16_f32 v18, v12, v13
	v_cvt_pk_bf16_f32 v19, v14, v15
	v_cvt_pk_bf16_f32 v20, v8, v9
	v_cvt_pk_bf16_f32 v21, v10, v11
	s_nop 0
	v_permlane16_swap_b32_e32 v18, v20
	v_permlane16_swap_b32_e32 v19, v21
	global_store_dwordx4 v[28:29], v[12:15], off
	global_store_dwordx4 v[28:29], v[8:11], off offset:64
	global_store_dwordx4 v[26:27], v[18:21], off
	s_nop 0
	v_pk_mul_f32 v[12:13], v[12:13], v[12:13]
	v_pk_mul_f32 v[8:9], v[8:9], v[8:9]
	v_pk_mul_f32 v[14:15], v[14:15], v[14:15]
	v_pk_mul_f32 v[10:11], v[10:11], v[10:11]
	v_add_f32_e32 v8, v8, v9
	v_add_f32_e32 v9, v12, v13
	v_add_f32_e32 v8, v10, v8
	v_add_f32_e32 v9, v14, v9
	v_add_f32_e32 v8, v11, v8
	v_add_f32_e32 v9, v15, v9
	v_add_f32_e32 v30, v9, v8
	v_pk_add_f32 v[0:1], v[0:1], v[208:209]
	v_pk_add_f32 v[2:3], v[2:3], v[210:211]
	v_pk_add_f32 v[4:5], v[4:5], v[212:213]
	v_pk_mul_f32 v[8:9], v[0:1], v[0:1]
	v_pk_add_f32 v[6:7], v[6:7], v[214:215]
	v_pk_mul_f32 v[10:11], v[2:3], v[2:3]
	v_pk_mul_f32 v[12:13], v[4:5], v[4:5]
	v_add_f32_e32 v8, v8, v9
	v_pk_mul_f32 v[14:15], v[6:7], v[6:7]
	v_add_f32_e32 v9, v12, v13
	v_add_f32_e32 v8, v10, v8
	v_add_f32_e32 v9, v14, v9
	v_add_f32_e32 v8, v11, v8
	v_add_f32_e32 v9, v15, v9
	v_add_f32_e32 v8, v30, v8
	v_add_f32_e32 v12, v8, v9
	ds_bpermute_b32 v13, v121, v12
	global_store_dwordx4 v[28:29], v[0:3], off offset:512
	v_cvt_pk_bf16_f32 v8, v0, v1
	v_cvt_pk_bf16_f32 v9, v2, v3
	v_cvt_pk_bf16_f32 v10, v4, v5
	s_waitcnt lgkmcnt(0)
	v_add_f32_e32 v0, v12, v13
	ds_bpermute_b32 v1, v120, v0
	v_cvt_pk_bf16_f32 v11, v6, v7
	v_permlane16_swap_b32_e32 v8, v10
	s_nop 0
	v_permlane16_swap_b32_e32 v9, v11
	global_store_dwordx4 v[28:29], v[4:7], off offset:576
	global_store_dwordx4 v[26:27], v[8:11], off offset:256
	s_and_saveexec_b64 s[22:23], vcc
	s_cbranch_execz .LBB0_1867
	v_lshlrev_b64 v[2:3], 7, v[16:17]
	v_lshl_add_u64 v[2:3], s[24:25], 0, v[2:3]
	s_waitcnt lgkmcnt(0)
	v_add_f32_e32 v0, v0, v1
	global_store_dword v[2:3], v0, off
	s_branch .LBB0_1867

; DEVINL int opaque_tid(int wv) { int t = (wv << 6) | (int)__builtin_amdgcn_mbcnt_hi(~0u, __builtin_amdgcn_mbcnt_lo(~0u, 0u)); asm volatile("" : "+v"(t)); return t; }
; DEVINL float shx(float v, int m, int lane) { return __int_as_float(__builtin_amdgcn_ds_bpermute((lane ^ m) << 2, __float_as_int(v))); }
; DEVINL void phase_gemm_res(const Params& p, const u16* A, int lda, const u16* B, int K, const float* resid, char* smem, int wv) {
;     ...
;   for (int tile = blockIdx.x; tile < NT * MT; tile += gridDim.x) {
;     const int tid = opaque_tid(wv), lane = tid & 63, wid = __builtin_amdgcn_readfirstlane(tid >> 6), wr = wid >> 2, wc = wid & 3, fr = lane & 15, fq = lane >> 4;
;     int pm, pn; tile_map(tile, MT, NT, pm, pn);
;     const int m0 = pm * 256, n0 = pn * 256;
;     f32x4 acc[2][2][4][2];
;     gemm8_mainloop(A, lda, B, K, K, m0, n0, acc, smem, tid);
;     if (tile + (int)gridDim.x < NT * MT) { int pm2, pn2; tile_map(tile + gridDim.x, MT, NT, pm2, pn2); gemm8_issue(A, lda, B, K, pm2 * 256, pn2 * 256, smem, tid); }
; #pragma unroll
;     for (int ai = 0; ai < 2; ++ai)
; #pragma unroll
;       for (int m = 0; m < 4; ++m) {
;         int row = m0 + ai * 128 + wr * 64 + m * 16 + fr;
;         size_t off = (size_t)row * DM + n0 + wc * 32 + fq * 4;
;         size_t offw = (size_t)row * DM + n0 + wc * 32 + (fq & 1) * 16 + (fq >> 1) * 8;
;         float ss = 0.f;
; #pragma unroll
;         for (int bj = 0; bj < 2; ++bj) {
;           f32x4 vv[2];
; #pragma unroll
;           for (int n = 0; n < 2; ++n) {
;             float4 rv = *(const float4*)(resid + off + bj * 128 + n * 16);
;             f32x4 v = acc[ai][bj][m][n];
;             v[0] += rv.x; v[1] += rv.y; v[2] += rv.z; v[3] += rv.w;
;             float4 ov; ov.x = v[0]; ov.y = v[1]; ov.z = v[2]; ov.w = v[3];
;             *(float4*)(out + off + bj * 128 + n * 16) = ov;
;             ss += sumsq4(v);
;             vv[n] = v;
;           }
;           *(u32x4*)(xb + offw + bj * 128) = widen2(vv[0], vv[1]);
;         }
;         ss += shx(ss, 16, lane); ss += shx(ss, 32, lane);
;         if (fq == 0) part[(size_t)row * 32 + pn * 4 + wc] = ss;
;       }
.LBB0_1992:
	s_ashr_i32 s23, s27, 2
	s_andn2_b32 s23, s23, 63
	v_or_b32_e32 v128, s23, v128
	s_bfe_u32 s34, s27, 0x20006
	v_add_u32_e32 v132, s22, v128
	s_lshl_b32 s22, s34, 5
	v_lshrrev_b32_e32 v128, 2, v151
	v_and_b32_e32 v130, 16, v151
	v_ashrrev_i32_e32 v133, 31, v132
	s_or_b32 s20, s20, s22
	v_and_b32_e32 v136, 12, v128
	v_and_or_b32 v128, v128, 8, v130
	v_lshlrev_b64 v[134:135], 11, v[132:133]
	v_lshlrev_b32_e32 v128, 1, v128
	v_lshl_add_u64 v[142:143], v[134:135], 0, s[20:21]
	v_lshl_add_u64 v[130:131], s[90:91], 0, v[128:129]
	v_lshl_add_u64 v[134:135], v[142:143], 2, s[92:93]
	v_lshlrev_b32_e32 v128, 2, v136
	v_lshl_add_u64 v[146:147], v[134:135], 0, v[128:129]
	global_load_dwordx4 v[200:203], v[146:147], off
	global_load_dwordx4 v[204:207], v[146:147], off offset:64
	global_load_dwordx4 v[208:211], v[146:147], off offset:512
	global_load_dwordx4 v[212:215], v[146:147], off offset:576
	v_lshl_add_u64 v[148:149], v[142:143], 1, v[130:131]
	s_lshl_b32 s22, s26, 2
	s_ashr_i32 s23, s22, 31
	s_lshl_b64 s[22:23], s[22:23], 2
	s_add_u32 s22, s60, s22
	s_addc_u32 s23, s61, s23
	s_lshl_b32 s26, s34, 2
	s_add_u32 s22, s22, s26
	s_addc_u32 s23, s23, 0
	s_waitcnt vmcnt(0)
	v_pk_add_f32 v[124:125], v[124:125], v[200:201]
	v_pk_add_f32 v[126:127], v[126:127], v[202:203]
	v_pk_add_f32 v[134:135], v[120:121], v[204:205]
	v_pk_add_f32 v[136:137], v[122:123], v[206:207]
	v_cvt_pk_bf16_f32 v120, v124, v125
	v_cvt_pk_bf16_f32 v121, v126, v127
	v_cvt_pk_bf16_f32 v122, v134, v135
	v_cvt_pk_bf16_f32 v123, v136, v137
	s_nop 0
	v_permlane16_swap_b32_e32 v120, v122
	v_permlane16_swap_b32_e32 v121, v123
	global_store_dwordx4 v[146:147], v[124:127], off
	global_store_dwordx4 v[146:147], v[134:137], off offset:64
	global_store_dwordx4 v[148:149], v[120:123], off
	s_nop 1
	v_and_b32_e32 v120, 63, v151
	v_lshlrev_b32_e32 v122, 2, v120
	v_cmp_gt_u32_e32 vcc, 16, v120
	v_xor_b32_e32 v121, 64, v122
	v_xor_b32_e32 v120, 0x80, v122
	v_pk_mul_f32 v[122:123], v[124:125], v[124:125]
	v_pk_mul_f32 v[124:125], v[126:127], v[126:127]
	v_pk_mul_f32 v[126:127], v[134:135], v[134:135]
	v_pk_mul_f32 v[134:135], v[136:137], v[136:137]
	v_add_f32_e32 v126, v126, v127
	v_add_f32_e32 v122, v122, v123
	v_add_f32_e32 v123, v134, v126
	v_add_f32_e32 v122, v124, v122
	v_add_f32_e32 v123, v135, v123
	v_add_f32_e32 v122, v125, v122
	v_add_f32_e32 v136, v122, v123
	v_pk_add_f32 v[112:113], v[112:113], v[208:209]
	v_pk_add_f32 v[114:115], v[114:115], v[210:211]
	v_pk_add_f32 v[116:117], v[116:117], v[212:213]
	v_pk_mul_f32 v[122:123], v[112:113], v[112:113]
	v_pk_add_f32 v[118:119], v[118:119], v[214:215]
	v_pk_mul_f32 v[124:125], v[114:115], v[114:115]
	v_pk_mul_f32 v[126:127], v[116:117], v[116:117]
	v_add_f32_e32 v122, v122, v123
	v_pk_mul_f32 v[134:135], v[118:119], v[118:119]
	v_add_f32_e32 v123, v126, v127
	v_add_f32_e32 v122, v124, v122
	v_add_f32_e32 v123, v134, v123
	v_add_f32_e32 v122, v125, v122
	v_add_f32_e32 v123, v135, v123
	v_add_f32_e32 v122, v136, v122
	v_add_f32_e32 v126, v122, v123
	ds_bpermute_b32 v127, v121, v126
	global_store_dwordx4 v[146:147], v[112:115], off offset:512
	v_cvt_pk_bf16_f32 v122, v112, v113
	v_cvt_pk_bf16_f32 v123, v114, v115
	v_cvt_pk_bf16_f32 v124, v116, v117
	s_waitcnt lgkmcnt(0)
	v_add_f32_e32 v112, v126, v127
	ds_bpermute_b32 v113, v120, v112
	v_cvt_pk_bf16_f32 v125, v118, v119
	v_permlane16_swap_b32_e32 v122, v124
	s_nop 0
	v_permlane16_swap_b32_e32 v123, v125
	global_store_dwordx4 v[146:147], v[116:119], off offset:576
	global_store_dwordx4 v[148:149], v[122:125], off offset:256
	s_and_saveexec_b64 s[26:27], vcc
	s_cbranch_execz .LBB0_1994
	v_lshlrev_b64 v[114:115], 7, v[132:133]
	v_lshl_add_u64 v[114:115], s[22:23], 0, v[114:115]
	s_waitcnt lgkmcnt(0)
	v_add_f32_e32 v112, v112, v113
	global_store_dword v[114:115], v112, off
.LBB0_1994:
	s_or_b64 exec, exec, s[26:27]
	v_or_b32_e32 v112, 16, v132
	s_waitcnt lgkmcnt(0)
	v_ashrrev_i32_e32 v113, 31, v112
	v_lshlrev_b64 v[114:115], 11, v[112:113]
	v_lshl_add_u64 v[118:119], v[114:115], 0, s[20:21]
	v_lshl_add_u64 v[114:115], v[118:119], 2, s[92:93]
	v_lshl_add_u64 v[126:127], v[114:115], 0, v[128:129]
	global_load_dwordx4 v[200:203], v[126:127], off
	global_load_dwordx4 v[204:207], v[126:127], off offset:64
	global_load_dwordx4 v[208:211], v[126:127], off offset:512
	global_load_dwordx4 v[212:215], v[126:127], off offset:576
	v_lshl_add_u64 v[118:119], v[118:119], 1, v[130:131]
	s_waitcnt vmcnt(0)
	v_pk_add_f32 v[108:109], v[108:109], v[200:201]
	v_pk_add_f32 v[110:111], v[110:111], v[202:203]
	v_pk_add_f32 v[104:105], v[104:105], v[204:205]
	v_pk_add_f32 v[106:107], v[106:107], v[206:207]
	v_cvt_pk_bf16_f32 v114, v108, v109
	v_cvt_pk_bf16_f32 v115, v110, v111
	v_cvt_pk_bf16_f32 v116, v104, v105
	v_cvt_pk_bf16_f32 v117, v106, v107
	s_nop 0
	v_permlane16_swap_b32_e32 v114, v116
	v_permlane16_swap_b32_e32 v115, v117
	global_store_dwordx4 v[126:127], v[108:111], off
	global_store_dwordx4 v[126:127], v[104:107], off offset:64
	global_store_dwordx4 v[118:119], v[114:117], off
	s_nop 0
	v_pk_mul_f32 v[108:109], v[108:109], v[108:109]
	v_pk_mul_f32 v[104:105], v[104:105], v[104:105]
	v_pk_mul_f32 v[110:111], v[110:111], v[110:111]
	v_pk_mul_f32 v[106:107], v[106:107], v[106:107]
	v_add_f32_e32 v104, v104, v105
	v_add_f32_e32 v105, v108, v109
	v_add_f32_e32 v104, v106, v104
	v_add_f32_e32 v105, v110, v105
	v_add_f32_e32 v104, v107, v104
	v_add_f32_e32 v105, v111, v105
	v_add_f32_e32 v133, v105, v104
	v_pk_add_f32 v[96:97], v[96:97], v[208:209]
	v_pk_add_f32 v[98:99], v[98:99], v[210:211]
	v_pk_add_f32 v[100:101], v[100:101], v[212:213]
	v_pk_mul_f32 v[104:105], v[96:97], v[96:97]
	v_pk_add_f32 v[102:103], v[102:103], v[214:215]
	v_pk_mul_f32 v[106:107], v[98:99], v[98:99]
	v_pk_mul_f32 v[108:109], v[100:101], v[100:101]
	v_add_f32_e32 v104, v104, v105
	v_pk_mul_f32 v[110:111], v[102:103], v[102:103]
	v_add_f32_e32 v105, v108, v109
	v_add_f32_e32 v104, v106, v104
	v_add_f32_e32 v105, v110, v105
	v_add_f32_e32 v104, v107, v104
	v_add_f32_e32 v105, v111, v105
	v_add_f32_e32 v104, v133, v104
	v_add_f32_e32 v108, v104, v105
	ds_bpermute_b32 v109, v121, v108
	global_store_dwordx4 v[126:127], v[96:99], off offset:512
	v_cvt_pk_bf16_f32 v104, v96, v97
	v_cvt_pk_bf16_f32 v105, v98, v99
	v_cvt_pk_bf16_f32 v106, v100, v101
	s_waitcnt lgkmcnt(0)
	v_add_f32_e32 v96, v108, v109
	ds_bpermute_b32 v97, v120, v96
	v_cvt_pk_bf16_f32 v107, v102, v103
	v_permlane16_swap_b32_e32 v104, v106
	s_nop 0
	v_permlane16_swap_b32_e32 v105, v107
	global_store_dwordx4 v[126:127], v[100:103], off offset:576
	global_store_dwordx4 v[118:119], v[104:107], off offset:256
	s_and_saveexec_b64 s[26:27], vcc
	s_cbranch_execz .LBB0_1996
	v_lshlrev_b64 v[98:99], 7, v[112:113]
	v_lshl_add_u64 v[98:99], s[22:23], 0, v[98:99]
	s_waitcnt lgkmcnt(0)
	v_add_f32_e32 v96, v96, v97
	global_store_dword v[98:99], v96, off
; DEVINL float shx(float v, int m, int lane) { return __int_as_float(__builtin_amdgcn_ds_bpermute((lane ^ m) << 2, __float_as_int(v))); }
; DEVINL void phase_gemm_res(const Params& p, const u16* A, int lda, const u16* B, int K, const float* resid, char* smem, int wv) {
;     ...
; #pragma unroll
;     for (int ai = 0; ai < 2; ++ai)
; #pragma unroll
;       for (int m = 0; m < 4; ++m) {
;         int row = m0 + ai * 128 + wr * 64 + m * 16 + fr;
;         size_t off = (size_t)row * DM + n0 + wc * 32 + fq * 4;
;         size_t offw = (size_t)row * DM + n0 + wc * 32 + (fq & 1) * 16 + (fq >> 1) * 8;
;         float ss = 0.f;
; #pragma unroll
;         for (int bj = 0; bj < 2; ++bj) {
;           f32x4 vv[2];
; #pragma unroll
;           for (int n = 0; n < 2; ++n) {
;             float4 rv = *(const float4*)(resid + off + bj * 128 + n * 16);
;             f32x4 v = acc[ai][bj][m][n];
;             v[0] += rv.x; v[1] += rv.y; v[2] += rv.z; v[3] += rv.w;
;             float4 ov; ov.x = v[0]; ov.y = v[1]; ov.z = v[2]; ov.w = v[3];
;             *(float4*)(out + off + bj * 128 + n * 16) = ov;
;             ss += sumsq4(v);
;             vv[n] = v;
;           }
;           *(u32x4*)(xb + offw + bj * 128) = widen2(vv[0], vv[1]);
;         }
;         ss += shx(ss, 16, lane); ss += shx(ss, 32, lane);
;         if (fq == 0) part[(size_t)row * 32 + pn * 4 + wc] = ss;
;       }
.LBB0_1996:
	s_or_b64 exec, exec, s[26:27]
	v_or_b32_e32 v96, 32, v132
	s_waitcnt lgkmcnt(0)
	v_ashrrev_i32_e32 v97, 31, v96
	v_lshlrev_b64 v[98:99], 11, v[96:97]
	v_lshl_add_u64 v[106:107], v[98:99], 0, s[20:21]
	v_lshl_add_u64 v[98:99], v[106:107], 2, s[92:93]
	v_lshl_add_u64 v[108:109], v[98:99], 0, v[128:129]
	global_load_dwordx4 v[200:203], v[108:109], off
	global_load_dwordx4 v[204:207], v[108:109], off offset:64
	global_load_dwordx4 v[208:211], v[108:109], off offset:512
	global_load_dwordx4 v[212:215], v[108:109], off offset:576
	v_lshl_add_u64 v[106:107], v[106:107], 1, v[130:131]
	s_waitcnt vmcnt(0)
	v_pk_add_f32 v[92:93], v[92:93], v[200:201]
	v_pk_add_f32 v[94:95], v[94:95], v[202:203]
	v_pk_add_f32 v[88:89], v[88:89], v[204:205]
	v_pk_add_f32 v[90:91], v[90:91], v[206:207]
	v_cvt_pk_bf16_f32 v98, v92, v93
	v_cvt_pk_bf16_f32 v99, v94, v95
	v_cvt_pk_bf16_f32 v100, v88, v89
	v_cvt_pk_bf16_f32 v101, v90, v91
	s_nop 0
	v_permlane16_swap_b32_e32 v98, v100
	v_permlane16_swap_b32_e32 v99, v101
	global_store_dwordx4 v[108:109], v[92:95], off
	global_store_dwordx4 v[108:109], v[88:91], off offset:64
	global_store_dwordx4 v[106:107], v[98:101], off
	s_nop 0
	v_pk_mul_f32 v[92:93], v[92:93], v[92:93]
	v_pk_mul_f32 v[88:89], v[88:89], v[88:89]
	v_pk_mul_f32 v[94:95], v[94:95], v[94:95]
	v_pk_mul_f32 v[90:91], v[90:91], v[90:91]
	v_add_f32_e32 v88, v88, v89
	v_add_f32_e32 v89, v92, v93
	v_add_f32_e32 v88, v90, v88
	v_add_f32_e32 v89, v94, v89
	v_add_f32_e32 v88, v91, v88
	v_add_f32_e32 v89, v95, v89
	v_add_f32_e32 v110, v89, v88
	v_pk_add_f32 v[80:81], v[80:81], v[208:209]
	v_pk_add_f32 v[82:83], v[82:83], v[210:211]
	v_pk_add_f32 v[84:85], v[84:85], v[212:213]
	v_pk_mul_f32 v[88:89], v[80:81], v[80:81]
	v_pk_add_f32 v[86:87], v[86:87], v[214:215]
	v_pk_mul_f32 v[90:91], v[82:83], v[82:83]
	v_pk_mul_f32 v[92:93], v[84:85], v[84:85]
	v_add_f32_e32 v88, v88, v89
	v_pk_mul_f32 v[94:95], v[86:87], v[86:87]
	v_add_f32_e32 v89, v92, v93
	v_add_f32_e32 v88, v90, v88
	v_add_f32_e32 v89, v94, v89
	v_add_f32_e32 v88, v91, v88
	v_add_f32_e32 v89, v95, v89
	v_add_f32_e32 v88, v110, v88
	v_add_f32_e32 v92, v88, v89
	ds_bpermute_b32 v93, v121, v92
	global_store_dwordx4 v[108:109], v[80:83], off offset:512
	v_cvt_pk_bf16_f32 v88, v80, v81
	v_cvt_pk_bf16_f32 v89, v82, v83
	v_cvt_pk_bf16_f32 v90, v84, v85
	s_waitcnt lgkmcnt(0)
	v_add_f32_e32 v80, v92, v93
	ds_bpermute_b32 v81, v120, v80
	v_cvt_pk_bf16_f32 v91, v86, v87
	v_permlane16_swap_b32_e32 v88, v90
	s_nop 0
	v_permlane16_swap_b32_e32 v89, v91
	global_store_dwordx4 v[108:109], v[84:87], off offset:576
	global_store_dwordx4 v[106:107], v[88:91], off offset:256
	s_and_saveexec_b64 s[26:27], vcc
	s_cbranch_execz .LBB0_1998
	v_lshlrev_b64 v[82:83], 7, v[96:97]
	v_lshl_add_u64 v[82:83], s[22:23], 0, v[82:83]
	s_waitcnt lgkmcnt(0)
	v_add_f32_e32 v80, v80, v81
	global_store_dword v[82:83], v80, off
.LBB0_1998:
	s_or_b64 exec, exec, s[26:27]
	v_or_b32_e32 v80, 48, v132
	s_waitcnt lgkmcnt(0)
	v_ashrrev_i32_e32 v81, 31, v80
	v_lshlrev_b64 v[82:83], 11, v[80:81]
	v_lshl_add_u64 v[90:91], v[82:83], 0, s[20:21]
	v_lshl_add_u64 v[82:83], v[90:91], 2, s[92:93]
	v_lshl_add_u64 v[92:93], v[82:83], 0, v[128:129]
	global_load_dwordx4 v[200:203], v[92:93], off
	global_load_dwordx4 v[204:207], v[92:93], off offset:64
	global_load_dwordx4 v[208:211], v[92:93], off offset:512
	global_load_dwordx4 v[212:215], v[92:93], off offset:576
	v_lshl_add_u64 v[90:91], v[90:91], 1, v[130:131]
	s_waitcnt vmcnt(0)
	v_pk_add_f32 v[76:77], v[76:77], v[200:201]
	v_pk_add_f32 v[78:79], v[78:79], v[202:203]
	v_pk_add_f32 v[72:73], v[72:73], v[204:205]
	v_pk_add_f32 v[74:75], v[74:75], v[206:207]
	v_cvt_pk_bf16_f32 v82, v76, v77
	v_cvt_pk_bf16_f32 v83, v78, v79
	v_cvt_pk_bf16_f32 v84, v72, v73
	v_cvt_pk_bf16_f32 v85, v74, v75
	s_nop 0
	v_permlane16_swap_b32_e32 v82, v84
	v_permlane16_swap_b32_e32 v83, v85
	global_store_dwordx4 v[92:93], v[76:79], off
	global_store_dwordx4 v[92:93], v[72:75], off offset:64
	global_store_dwordx4 v[90:91], v[82:85], off
	s_nop 0
	v_pk_mul_f32 v[76:77], v[76:77], v[76:77]
	v_pk_mul_f32 v[72:73], v[72:73], v[72:73]
	v_pk_mul_f32 v[78:79], v[78:79], v[78:79]
	v_pk_mul_f32 v[74:75], v[74:75], v[74:75]
	v_add_f32_e32 v72, v72, v73
	v_add_f32_e32 v73, v76, v77
	v_add_f32_e32 v72, v74, v72
	v_add_f32_e32 v73, v78, v73
	v_add_f32_e32 v72, v75, v72
	v_add_f32_e32 v73, v79, v73
	v_add_f32_e32 v94, v73, v72
	v_pk_add_f32 v[64:65], v[64:65], v[208:209]
	v_pk_add_f32 v[66:67], v[66:67], v[210:211]
	v_pk_add_f32 v[68:69], v[68:69], v[212:213]
	v_pk_mul_f32 v[72:73], v[64:65], v[64:65]
	v_pk_add_f32 v[70:71], v[70:71], v[214:215]
	v_pk_mul_f32 v[74:75], v[66:67], v[66:67]
	v_pk_mul_f32 v[76:77], v[68:69], v[68:69]
	v_add_f32_e32 v72, v72, v73
	v_pk_mul_f32 v[78:79], v[70:71], v[70:71]
	v_add_f32_e32 v73, v76, v77
	v_add_f32_e32 v72, v74, v72
	v_add_f32_e32 v73, v78, v73
	v_add_f32_e32 v72, v75, v72
	v_add_f32_e32 v73, v79, v73
	v_add_f32_e32 v72, v94, v72
	v_add_f32_e32 v76, v72, v73
	ds_bpermute_b32 v77, v121, v76
	global_store_dwordx4 v[92:93], v[64:67], off offset:512
	v_cvt_pk_bf16_f32 v72, v64, v65
	v_cvt_pk_bf16_f32 v73, v66, v67
	v_cvt_pk_bf16_f32 v74, v68, v69
	s_waitcnt lgkmcnt(0)
	v_add_f32_e32 v64, v76, v77
	ds_bpermute_b32 v65, v120, v64
	v_cvt_pk_bf16_f32 v75, v70, v71
	v_permlane16_swap_b32_e32 v72, v74
	s_nop 0
	v_permlane16_swap_b32_e32 v73, v75
	global_store_dwordx4 v[92:93], v[68:71], off offset:576
	global_store_dwordx4 v[90:91], v[72:75], off offset:256
	s_and_saveexec_b64 s[26:27], vcc
	s_cbranch_execz .LBB0_2000
	v_lshlrev_b64 v[66:67], 7, v[80:81]
	v_lshl_add_u64 v[66:67], s[22:23], 0, v[66:67]
	s_waitcnt lgkmcnt(0)
	v_add_f32_e32 v64, v64, v65
	global_store_dword v[66:67], v64, off
; DEVINL float shx(float v, int m, int lane) { return __int_as_float(__builtin_amdgcn_ds_bpermute((lane ^ m) << 2, __float_as_int(v))); }
; DEVINL void phase_gemm_res(const Params& p, const u16* A, int lda, const u16* B, int K, const float* resid, char* smem, int wv) {
;     ...
; #pragma unroll
;     for (int ai = 0; ai < 2; ++ai)
; #pragma unroll
;       for (int m = 0; m < 4; ++m) {
;         int row = m0 + ai * 128 + wr * 64 + m * 16 + fr;
;         size_t off = (size_t)row * DM + n0 + wc * 32 + fq * 4;
;         size_t offw = (size_t)row * DM + n0 + wc * 32 + (fq & 1) * 16 + (fq >> 1) * 8;
;         float ss = 0.f;
; #pragma unroll
;         for (int bj = 0; bj < 2; ++bj) {
;           f32x4 vv[2];
; #pragma unroll
;           for (int n = 0; n < 2; ++n) {
;             float4 rv = *(const float4*)(resid + off + bj * 128 + n * 16);
;             f32x4 v = acc[ai][bj][m][n];
;             v[0] += rv.x; v[1] += rv.y; v[2] += rv.z; v[3] += rv.w;
;             float4 ov; ov.x = v[0]; ov.y = v[1]; ov.z = v[2]; ov.w = v[3];
;             *(float4*)(out + off + bj * 128 + n * 16) = ov;
;             ss += sumsq4(v);
;             vv[n] = v;
;           }
;           *(u32x4*)(xb + offw + bj * 128) = widen2(vv[0], vv[1]);
;         }
;         ss += shx(ss, 16, lane); ss += shx(ss, 32, lane);
;         if (fq == 0) part[(size_t)row * 32 + pn * 4 + wc] = ss;
;       }
.LBB0_2000:
	s_or_b64 exec, exec, s[26:27]
	v_add_u32_e32 v64, 0x80, v132
	s_waitcnt lgkmcnt(0)
	v_ashrrev_i32_e32 v65, 31, v64
	v_lshlrev_b64 v[66:67], 11, v[64:65]
	v_lshl_add_u64 v[74:75], v[66:67], 0, s[20:21]
	v_lshl_add_u64 v[66:67], v[74:75], 2, s[92:93]
	v_lshl_add_u64 v[76:77], v[66:67], 0, v[128:129]
	global_load_dwordx4 v[200:203], v[76:77], off
	global_load_dwordx4 v[204:207], v[76:77], off offset:64
	global_load_dwordx4 v[208:211], v[76:77], off offset:512
	global_load_dwordx4 v[212:215], v[76:77], off offset:576
	v_lshl_add_u64 v[74:75], v[74:75], 1, v[130:131]
	s_waitcnt vmcnt(0)
	v_pk_add_f32 v[60:61], v[60:61], v[200:201]
	v_pk_add_f32 v[62:63], v[62:63], v[202:203]
	v_pk_add_f32 v[56:57], v[56:57], v[204:205]
	v_pk_add_f32 v[58:59], v[58:59], v[206:207]
	v_cvt_pk_bf16_f32 v66, v60, v61
	v_cvt_pk_bf16_f32 v67, v62, v63
	v_cvt_pk_bf16_f32 v68, v56, v57
	v_cvt_pk_bf16_f32 v69, v58, v59
	s_nop 0
	v_permlane16_swap_b32_e32 v66, v68
	v_permlane16_swap_b32_e32 v67, v69
	global_store_dwordx4 v[76:77], v[60:63], off
	global_store_dwordx4 v[76:77], v[56:59], off offset:64
	global_store_dwordx4 v[74:75], v[66:69], off
	s_nop 0
	v_pk_mul_f32 v[60:61], v[60:61], v[60:61]
	v_pk_mul_f32 v[56:57], v[56:57], v[56:57]
	v_pk_mul_f32 v[62:63], v[62:63], v[62:63]
	v_pk_mul_f32 v[58:59], v[58:59], v[58:59]
	v_add_f32_e32 v56, v56, v57
	v_add_f32_e32 v57, v60, v61
	v_add_f32_e32 v56, v58, v56
	v_add_f32_e32 v57, v62, v57
	v_add_f32_e32 v56, v59, v56
	v_add_f32_e32 v57, v63, v57
	v_add_f32_e32 v78, v57, v56
	v_pk_add_f32 v[48:49], v[48:49], v[208:209]
	v_pk_add_f32 v[50:51], v[50:51], v[210:211]
	v_pk_add_f32 v[52:53], v[52:53], v[212:213]
	v_pk_mul_f32 v[56:57], v[48:49], v[48:49]
	v_pk_add_f32 v[54:55], v[54:55], v[214:215]
	v_pk_mul_f32 v[58:59], v[50:51], v[50:51]
	v_pk_mul_f32 v[60:61], v[52:53], v[52:53]
	v_add_f32_e32 v56, v56, v57
	v_pk_mul_f32 v[62:63], v[54:55], v[54:55]
	v_add_f32_e32 v57, v60, v61
	v_add_f32_e32 v56, v58, v56
	v_add_f32_e32 v57, v62, v57
	v_add_f32_e32 v56, v59, v56
	v_add_f32_e32 v57, v63, v57
	v_add_f32_e32 v56, v78, v56
	v_add_f32_e32 v60, v56, v57
	ds_bpermute_b32 v61, v121, v60
	global_store_dwordx4 v[76:77], v[48:51], off offset:512
	v_cvt_pk_bf16_f32 v56, v48, v49
	v_cvt_pk_bf16_f32 v57, v50, v51
	v_cvt_pk_bf16_f32 v58, v52, v53
	s_waitcnt lgkmcnt(0)
	v_add_f32_e32 v48, v60, v61
	ds_bpermute_b32 v49, v120, v48
	v_cvt_pk_bf16_f32 v59, v54, v55
	v_permlane16_swap_b32_e32 v56, v58
	s_nop 0
	v_permlane16_swap_b32_e32 v57, v59
	global_store_dwordx4 v[76:77], v[52:55], off offset:576
	global_store_dwordx4 v[74:75], v[56:59], off offset:256
	s_and_saveexec_b64 s[26:27], vcc
	s_cbranch_execz .LBB0_2002
	v_lshlrev_b64 v[50:51], 7, v[64:65]
	v_lshl_add_u64 v[50:51], s[22:23], 0, v[50:51]
	s_waitcnt lgkmcnt(0)
	v_add_f32_e32 v48, v48, v49
	global_store_dword v[50:51], v48, off
.LBB0_2002:
	s_or_b64 exec, exec, s[26:27]
	v_add_u32_e32 v48, 0x90, v132
	s_waitcnt lgkmcnt(0)
	v_ashrrev_i32_e32 v49, 31, v48
	v_lshlrev_b64 v[50:51], 11, v[48:49]
	v_lshl_add_u64 v[58:59], v[50:51], 0, s[20:21]
	v_lshl_add_u64 v[50:51], v[58:59], 2, s[92:93]
	v_lshl_add_u64 v[60:61], v[50:51], 0, v[128:129]
	global_load_dwordx4 v[200:203], v[60:61], off
	global_load_dwordx4 v[204:207], v[60:61], off offset:64
	global_load_dwordx4 v[208:211], v[60:61], off offset:512
	global_load_dwordx4 v[212:215], v[60:61], off offset:576
	v_lshl_add_u64 v[58:59], v[58:59], 1, v[130:131]
	s_waitcnt vmcnt(0)
	v_pk_add_f32 v[44:45], v[44:45], v[200:201]
	v_pk_add_f32 v[46:47], v[46:47], v[202:203]
	v_pk_add_f32 v[40:41], v[40:41], v[204:205]
	v_pk_add_f32 v[42:43], v[42:43], v[206:207]
	v_cvt_pk_bf16_f32 v50, v44, v45
	v_cvt_pk_bf16_f32 v51, v46, v47
	v_cvt_pk_bf16_f32 v52, v40, v41
	v_cvt_pk_bf16_f32 v53, v42, v43
	s_nop 0
	v_permlane16_swap_b32_e32 v50, v52
	v_permlane16_swap_b32_e32 v51, v53
	global_store_dwordx4 v[60:61], v[44:47], off
	global_store_dwordx4 v[60:61], v[40:43], off offset:64
	global_store_dwordx4 v[58:59], v[50:53], off
	s_nop 0
	v_pk_mul_f32 v[44:45], v[44:45], v[44:45]
	v_pk_mul_f32 v[40:41], v[40:41], v[40:41]
	v_pk_mul_f32 v[46:47], v[46:47], v[46:47]
	v_pk_mul_f32 v[42:43], v[42:43], v[42:43]
	v_add_f32_e32 v40, v40, v41
	v_add_f32_e32 v41, v44, v45
	v_add_f32_e32 v40, v42, v40
	v_add_f32_e32 v41, v46, v41
	v_add_f32_e32 v40, v43, v40
	v_add_f32_e32 v41, v47, v41
	v_add_f32_e32 v62, v41, v40
	v_pk_add_f32 v[32:33], v[32:33], v[208:209]
	v_pk_add_f32 v[34:35], v[34:35], v[210:211]
	v_pk_add_f32 v[36:37], v[36:37], v[212:213]
	v_pk_mul_f32 v[40:41], v[32:33], v[32:33]
	v_pk_add_f32 v[38:39], v[38:39], v[214:215]
	v_pk_mul_f32 v[42:43], v[34:35], v[34:35]
	v_pk_mul_f32 v[44:45], v[36:37], v[36:37]
	v_add_f32_e32 v40, v40, v41
	v_pk_mul_f32 v[46:47], v[38:39], v[38:39]
	v_add_f32_e32 v41, v44, v45
	v_add_f32_e32 v40, v42, v40
	v_add_f32_e32 v41, v46, v41
	v_add_f32_e32 v40, v43, v40
	v_add_f32_e32 v41, v47, v41
	v_add_f32_e32 v40, v62, v40
	v_add_f32_e32 v44, v40, v41
	ds_bpermute_b32 v45, v121, v44
	global_store_dwordx4 v[60:61], v[32:35], off offset:512
	v_cvt_pk_bf16_f32 v40, v32, v33
	v_cvt_pk_bf16_f32 v41, v34, v35
	v_cvt_pk_bf16_f32 v42, v36, v37
	s_waitcnt lgkmcnt(0)
	v_add_f32_e32 v32, v44, v45
	ds_bpermute_b32 v33, v120, v32
	v_cvt_pk_bf16_f32 v43, v38, v39
	v_permlane16_swap_b32_e32 v40, v42
	s_nop 0
	v_permlane16_swap_b32_e32 v41, v43
	global_store_dwordx4 v[60:61], v[36:39], off offset:576
	global_store_dwordx4 v[58:59], v[40:43], off offset:256
	s_and_saveexec_b64 s[26:27], vcc
	s_cbranch_execz .LBB0_2004
	v_lshlrev_b64 v[34:35], 7, v[48:49]
	v_lshl_add_u64 v[34:35], s[22:23], 0, v[34:35]
	s_waitcnt lgkmcnt(0)
	v_add_f32_e32 v32, v32, v33
	global_store_dword v[34:35], v32, off
; DEVINL float shx(float v, int m, int lane) { return __int_as_float(__builtin_amdgcn_ds_bpermute((lane ^ m) << 2, __float_as_int(v))); }
; DEVINL void phase_gemm_res(const Params& p, const u16* A, int lda, const u16* B, int K, const float* resid, char* smem, int wv) {
;     ...
; #pragma unroll
;     for (int ai = 0; ai < 2; ++ai)
; #pragma unroll
;       for (int m = 0; m < 4; ++m) {
;         int row = m0 + ai * 128 + wr * 64 + m * 16 + fr;
;         size_t off = (size_t)row * DM + n0 + wc * 32 + fq * 4;
;         size_t offw = (size_t)row * DM + n0 + wc * 32 + (fq & 1) * 16 + (fq >> 1) * 8;
;         float ss = 0.f;
; #pragma unroll
;         for (int bj = 0; bj < 2; ++bj) {
;           f32x4 vv[2];
; #pragma unroll
;           for (int n = 0; n < 2; ++n) {
;             float4 rv = *(const float4*)(resid + off + bj * 128 + n * 16);
;             f32x4 v = acc[ai][bj][m][n];
;             v[0] += rv.x; v[1] += rv.y; v[2] += rv.z; v[3] += rv.w;
;             float4 ov; ov.x = v[0]; ov.y = v[1]; ov.z = v[2]; ov.w = v[3];
;             *(float4*)(out + off + bj * 128 + n * 16) = ov;
;             ss += sumsq4(v);
;             vv[n] = v;
;           }
;           *(u32x4*)(xb + offw + bj * 128) = widen2(vv[0], vv[1]);
;         }
;         ss += shx(ss, 16, lane); ss += shx(ss, 32, lane);
;         if (fq == 0) part[(size_t)row * 32 + pn * 4 + wc] = ss;
;       }
.LBB0_2004:
	s_or_b64 exec, exec, s[26:27]
	v_add_u32_e32 v32, 0xa0, v132
	s_waitcnt lgkmcnt(0)
	v_ashrrev_i32_e32 v33, 31, v32
	v_lshlrev_b64 v[34:35], 11, v[32:33]
	v_lshl_add_u64 v[42:43], v[34:35], 0, s[20:21]
	v_lshl_add_u64 v[34:35], v[42:43], 2, s[92:93]
	v_lshl_add_u64 v[44:45], v[34:35], 0, v[128:129]
	global_load_dwordx4 v[200:203], v[44:45], off
	global_load_dwordx4 v[204:207], v[44:45], off offset:64
	global_load_dwordx4 v[208:211], v[44:45], off offset:512
	global_load_dwordx4 v[212:215], v[44:45], off offset:576
	v_lshl_add_u64 v[42:43], v[42:43], 1, v[130:131]
	s_waitcnt vmcnt(0)
	v_pk_add_f32 v[28:29], v[28:29], v[200:201]
	v_pk_add_f32 v[30:31], v[30:31], v[202:203]
	v_pk_add_f32 v[24:25], v[24:25], v[204:205]
	v_pk_add_f32 v[26:27], v[26:27], v[206:207]
	v_cvt_pk_bf16_f32 v34, v28, v29
	v_cvt_pk_bf16_f32 v35, v30, v31
	v_cvt_pk_bf16_f32 v36, v24, v25
	v_cvt_pk_bf16_f32 v37, v26, v27
	s_nop 0
	v_permlane16_swap_b32_e32 v34, v36
	v_permlane16_swap_b32_e32 v35, v37
	global_store_dwordx4 v[44:45], v[28:31], off
	global_store_dwordx4 v[44:45], v[24:27], off offset:64
	global_store_dwordx4 v[42:43], v[34:37], off
	s_nop 0
	v_pk_mul_f32 v[28:29], v[28:29], v[28:29]
	v_pk_mul_f32 v[24:25], v[24:25], v[24:25]
	v_pk_mul_f32 v[30:31], v[30:31], v[30:31]
	v_pk_mul_f32 v[26:27], v[26:27], v[26:27]
	v_add_f32_e32 v24, v24, v25
	v_add_f32_e32 v25, v28, v29
	v_add_f32_e32 v24, v26, v24
	v_add_f32_e32 v25, v30, v25
	v_add_f32_e32 v24, v27, v24
	v_add_f32_e32 v25, v31, v25
	v_add_f32_e32 v46, v25, v24
	v_pk_add_f32 v[16:17], v[16:17], v[208:209]
	v_pk_add_f32 v[18:19], v[18:19], v[210:211]
	v_pk_add_f32 v[20:21], v[20:21], v[212:213]
	v_pk_mul_f32 v[24:25], v[16:17], v[16:17]
	v_pk_add_f32 v[22:23], v[22:23], v[214:215]
	v_pk_mul_f32 v[26:27], v[18:19], v[18:19]
	v_pk_mul_f32 v[28:29], v[20:21], v[20:21]
	v_add_f32_e32 v24, v24, v25
	v_pk_mul_f32 v[30:31], v[22:23], v[22:23]
	v_add_f32_e32 v25, v28, v29
	v_add_f32_e32 v24, v26, v24
	v_add_f32_e32 v25, v30, v25
	v_add_f32_e32 v24, v27, v24
	v_add_f32_e32 v25, v31, v25
	v_add_f32_e32 v24, v46, v24
	v_add_f32_e32 v28, v24, v25
	ds_bpermute_b32 v29, v121, v28
	global_store_dwordx4 v[44:45], v[16:19], off offset:512
	v_cvt_pk_bf16_f32 v24, v16, v17
	v_cvt_pk_bf16_f32 v25, v18, v19
	v_cvt_pk_bf16_f32 v26, v20, v21
	s_waitcnt lgkmcnt(0)
	v_add_f32_e32 v16, v28, v29
	ds_bpermute_b32 v17, v120, v16
	v_cvt_pk_bf16_f32 v27, v22, v23
	v_permlane16_swap_b32_e32 v24, v26
	s_nop 0
	v_permlane16_swap_b32_e32 v25, v27
	global_store_dwordx4 v[44:45], v[20:23], off offset:576
	global_store_dwordx4 v[42:43], v[24:27], off offset:256
	s_and_saveexec_b64 s[26:27], vcc
	s_cbranch_execz .LBB0_2006
	v_lshlrev_b64 v[18:19], 7, v[32:33]
	v_lshl_add_u64 v[18:19], s[22:23], 0, v[18:19]
	s_waitcnt lgkmcnt(0)
	v_add_f32_e32 v16, v16, v17
	global_store_dword v[18:19], v16, off
.LBB0_2006:
	s_or_b64 exec, exec, s[26:27]
	v_add_u32_e32 v16, 0xb0, v132
	s_waitcnt lgkmcnt(0)
	v_ashrrev_i32_e32 v17, 31, v16
	v_lshlrev_b64 v[18:19], 11, v[16:17]
	v_lshl_add_u64 v[26:27], v[18:19], 0, s[20:21]
	v_lshl_add_u64 v[18:19], v[26:27], 2, s[92:93]
	v_lshl_add_u64 v[28:29], v[18:19], 0, v[128:129]
	global_load_dwordx4 v[200:203], v[28:29], off
	global_load_dwordx4 v[204:207], v[28:29], off offset:64
	global_load_dwordx4 v[208:211], v[28:29], off offset:512
	global_load_dwordx4 v[212:215], v[28:29], off offset:576
	v_lshl_add_u64 v[26:27], v[26:27], 1, v[130:131]
	s_waitcnt vmcnt(0)
	v_pk_add_f32 v[12:13], v[12:13], v[200:201]
	v_pk_add_f32 v[14:15], v[14:15], v[202:203]
	v_pk_add_f32 v[8:9], v[8:9], v[204:205]
	v_pk_add_f32 v[10:11], v[10:11], v[206:207]
	v_cvt_pk_bf16_f32 v18, v12, v13
	v_cvt_pk_bf16_f32 v19, v14, v15
	v_cvt_pk_bf16_f32 v20, v8, v9
	v_cvt_pk_bf16_f32 v21, v10, v11
	s_nop 0
	v_permlane16_swap_b32_e32 v18, v20
	v_permlane16_swap_b32_e32 v19, v21
	global_store_dwordx4 v[28:29], v[12:15], off
	global_store_dwordx4 v[28:29], v[8:11], off offset:64
	global_store_dwordx4 v[26:27], v[18:21], off
	s_nop 0
	v_pk_mul_f32 v[12:13], v[12:13], v[12:13]
	v_pk_mul_f32 v[8:9], v[8:9], v[8:9]
	v_pk_mul_f32 v[14:15], v[14:15], v[14:15]
	v_pk_mul_f32 v[10:11], v[10:11], v[10:11]
	v_add_f32_e32 v8, v8, v9
	v_add_f32_e32 v9, v12, v13
	v_add_f32_e32 v8, v10, v8
	v_add_f32_e32 v9, v14, v9
	v_add_f32_e32 v8, v11, v8
	v_add_f32_e32 v9, v15, v9
	v_add_f32_e32 v30, v9, v8
	v_pk_add_f32 v[0:1], v[0:1], v[208:209]
	v_pk_add_f32 v[2:3], v[2:3], v[210:211]
	v_pk_add_f32 v[4:5], v[4:5], v[212:213]
	v_pk_mul_f32 v[8:9], v[0:1], v[0:1]
	v_pk_add_f32 v[6:7], v[6:7], v[214:215]
	v_pk_mul_f32 v[10:11], v[2:3], v[2:3]
	v_pk_mul_f32 v[12:13], v[4:5], v[4:5]
	v_add_f32_e32 v8, v8, v9
	v_pk_mul_f32 v[14:15], v[6:7], v[6:7]
	v_add_f32_e32 v9, v12, v13
	v_add_f32_e32 v8, v10, v8
	v_add_f32_e32 v9, v14, v9
	v_add_f32_e32 v8, v11, v8
	v_add_f32_e32 v9, v15, v9
	v_add_f32_e32 v8, v30, v8
	v_add_f32_e32 v12, v8, v9
	ds_bpermute_b32 v13, v121, v12
	global_store_dwordx4 v[28:29], v[0:3], off offset:512
	v_cvt_pk_bf16_f32 v8, v0, v1
	v_cvt_pk_bf16_f32 v9, v2, v3
	v_cvt_pk_bf16_f32 v10, v4, v5
	s_waitcnt lgkmcnt(0)
	v_add_f32_e32 v0, v12, v13
	ds_bpermute_b32 v1, v120, v0
	v_cvt_pk_bf16_f32 v11, v6, v7
	v_permlane16_swap_b32_e32 v8, v10
	s_nop 0
	v_permlane16_swap_b32_e32 v9, v11
	global_store_dwordx4 v[28:29], v[4:7], off offset:576
	global_store_dwordx4 v[26:27], v[8:11], off offset:256
	s_and_saveexec_b64 s[20:21], vcc
	s_cbranch_execz .LBB0_1983
	v_lshlrev_b64 v[2:3], 7, v[16:17]
	v_lshl_add_u64 v[2:3], s[22:23], 0, v[2:3]
	s_waitcnt lgkmcnt(0)
	v_add_f32_e32 v0, v0, v1
	global_store_dword v[2:3], v0, off
	s_branch .LBB0_1983
